# attention loop rewritten by hand: 16 keys per block, DPP reductions, K prefetch before PV
# speedup vs baseline: 1.0047x; 1.0047x over previous
; __device__ __forceinline__ void unpack8(u32x4 w, float* v) { v[0] = bflo(w.x); v[1] = bfhi(w.x); v[2] = bflo(w.y); v[3] = bfhi(w.y); v[4] = bflo(w.z); v[5] = bfhi(w.z); v[6] = bflo(w.w); v[7] = bfhi(w.w); }
; __device__ __forceinline__ void attn_phase(const Args& a, unsigned char* lds, int lane, int wave) {
;     ...
;     for (int t = gw; t < TT; t += NGW) {
;         const bool sample = t >= TP; const int bb = sample ? (t - TP) >> 6 : 0;
;         const int c = t >> 6; const int L = sample ? 1088 : 64 * (c + 1);
;         const int nsel = min(256, L);
;         const unsigned* cand = CAND + (size_t)t * 256;
; #pragma unroll
;         for (int j = 0; j < 4; ++j) { const int i = j * 64 + lane; if (i < nsel) sel[i] = cand[i] & 0x3FFFu; }
;         bf16_t* qp = P + (size_t)t * NP + lane * 16;
;         float q[16]; unpack8(*(const u32x4*)qp, q); unpack8(*(const u32x4*)(qp + 8), q + 8);
;         float mx = -INFINITY, l = 0.f, o[16];
; #pragma unroll
;         for (int d = 0; d < 16; ++d) o[d] = 0.f;
;         for (int j = 0; j < nsel; j += 8) {
;             const u32x4 ida = *(const u32x4*)(sel + j), idb = *(const u32x4*)(sel + j + 4);
;             u32x4 kk[8], vv[8];
; #pragma unroll
;             for (int i = 0; i < 8; ++i) { const int idx = (int)(i < 4 ? ida[i & 3] : idb[i & 3]); const unsigned char* kp;
;                 if (!sample) kp = KV8 + (size_t)idx * 2048;
;                 else if (idx < 1024) kp = CKV8 + (size_t)(bb * 1024 + idx) * 2048;
;                 else kp = KV8 + (size_t)(TP + bb * 64 + idx - 1024) * 2048;
;                 kk[i] = *(const u32x4*)(kp + lane * 16); vv[i] = *(const u32x4*)(kp + 1024 + lane * 16); }
.Lat_q:
	s_and_b32 s0, s2, 0xffffffc0
	s_add_i32 s0, s0, 64
	s_min_i32 s30, s0, 0x100
	s_lshl_b32 s8, s2, 10
	s_add_u32 s8, s26, s8
	s_addc_u32 s9, s27, 0
	global_load_dword v0, v99, s[8:9]
	global_load_dword v1, v99, s[8:9] offset:256
	global_load_dword v2, v99, s[8:9] offset:512
	global_load_dword v3, v99, s[8:9] offset:768
	v_mad_i64_i32 v[60:61], s[10:11], s2, v98, v[58:59]
	s_mov_b64 s[98:99], s[4:5]
	s_mov_b64 s[100:101], s[4:5]
	s_cmpk_gt_i32 s2, 0x3fff
	s_cbranch_scc0 .Lat_ns
	s_movk_i32 s30, 0x100
	s_add_i32 s8, s2, 0xffffc000
	s_and_b32 s9, s8, 0xffffffc0
	s_addk_i32 s9, 0x3c00
	s_lshl_b32 s9, s9, 11
	s_add_u32 s100, s4, s9
	s_addc_u32 s101, s5, 0
	s_lshl_b32 s8, s8, 4
	s_and_b32 s8, s8, 0xfffffc00
	s_lshl_b32 s8, s8, 11
	s_add_u32 s98, s6, s8
	s_addc_u32 s99, s7, 0
.Lat_ns:
	global_load_dwordx4 v[4:7], v[60:61], off
	global_load_dwordx4 v[8:11], v[60:61], off offset:16
	s_add_i32 s31, s29, -16
	s_lshr_b32 s3, s30, 4
	s_waitcnt vmcnt(2)
	v_and_b32_e32 v0, 0x3fff, v0
	v_and_b32_e32 v1, 0x3fff, v1
	v_and_b32_e32 v2, 0x3fff, v2
	v_and_b32_e32 v3, 0x3fff, v3
	ds_write_b32 v94, v0
	ds_write_b32 v94, v1 offset:256
	ds_write_b32 v94, v2 offset:512
	ds_write_b32 v94, v3 offset:768
	v_mov_b32_e32 v246, s31
	ds_read_b128 v[204:207], v246
	ds_read_b128 v[208:211], v246 offset:16
	ds_read_b128 v[212:215], v246 offset:32
	ds_read_b128 v[216:219], v246 offset:48
	v_mov_b32_e32 v62, 0
	v_mov_b32_e32 v63, 0
	v_mov_b32_e32 v64, 0
	v_mov_b32_e32 v65, 0
	v_mov_b32_e32 v66, 0
	v_mov_b32_e32 v67, 0
	v_mov_b32_e32 v68, 0
	v_mov_b32_e32 v69, 0
	v_mov_b32_e32 v70, 0
	v_mov_b32_e32 v71, 0
	v_mov_b32_e32 v72, 0
	v_mov_b32_e32 v73, 0
	v_mov_b32_e32 v74, 0
	v_mov_b32_e32 v75, 0
	v_mov_b32_e32 v76, 0
	v_mov_b32_e32 v77, 0
	v_mov_b32_e32 v108, 0
	v_mov_b32_e32 v109, 0xff800000
	s_waitcnt vmcnt(0)
	v_lshlrev_b32_e32 v78, 16, v4
	v_and_b32_e32 v79, 0xffff0000, v4
	v_lshlrev_b32_e32 v80, 16, v5
	v_and_b32_e32 v81, 0xffff0000, v5
	v_lshlrev_b32_e32 v82, 16, v6
	v_and_b32_e32 v83, 0xffff0000, v6
	v_lshlrev_b32_e32 v84, 16, v7
	v_and_b32_e32 v85, 0xffff0000, v7
	v_lshlrev_b32_e32 v86, 16, v8
	v_and_b32_e32 v87, 0xffff0000, v8
	v_lshlrev_b32_e32 v88, 16, v9
	v_and_b32_e32 v89, 0xffff0000, v9
	v_lshlrev_b32_e32 v90, 16, v10
	v_and_b32_e32 v91, 0xffff0000, v10
	v_lshlrev_b32_e32 v92, 16, v11
	v_and_b32_e32 v93, 0xffff0000, v11
	s_waitcnt lgkmcnt(0)
	v_readfirstlane_b32 s8, v204
	v_readfirstlane_b32 s9, v205
	v_readfirstlane_b32 s10, v206
	v_readfirstlane_b32 s11, v207
	v_readfirstlane_b32 s12, v208
	v_readfirstlane_b32 s13, v209
	v_readfirstlane_b32 s14, v210
	v_readfirstlane_b32 s15, v211
	v_readfirstlane_b32 s16, v212
	v_readfirstlane_b32 s17, v213
	v_readfirstlane_b32 s18, v214
	v_readfirstlane_b32 s19, v215
	v_readfirstlane_b32 s20, v216
	v_readfirstlane_b32 s21, v217
	v_readfirstlane_b32 s22, v218
	v_readfirstlane_b32 s23, v219
	s_cmp_lt_u32 s8, 0x400
	s_cselect_b32 s24, s98, s100
	s_cselect_b32 s25, s99, s101
	s_lshl_b32 s8, s8, 11
	s_add_u32 s24, s24, s8
	s_addc_u32 s25, s25, 0
	global_load_dwordx4 v[132:135], v56, s[24:25]
	s_cmp_lt_u32 s9, 0x400
	s_cselect_b32 s24, s98, s100
	s_cselect_b32 s25, s99, s101
	s_lshl_b32 s9, s9, 11
	s_add_u32 s24, s24, s9
	s_addc_u32 s25, s25, 0
	global_load_dwordx4 v[136:139], v56, s[24:25]
	s_cmp_lt_u32 s10, 0x400
	s_cselect_b32 s24, s98, s100
	s_cselect_b32 s25, s99, s101
	s_lshl_b32 s10, s10, 11
	s_add_u32 s24, s24, s10
	s_addc_u32 s25, s25, 0
	global_load_dwordx4 v[140:143], v56, s[24:25]
	s_cmp_lt_u32 s11, 0x400
	s_cselect_b32 s24, s98, s100
	s_cselect_b32 s25, s99, s101
	s_lshl_b32 s11, s11, 11
	s_add_u32 s24, s24, s11
	s_addc_u32 s25, s25, 0
	global_load_dwordx4 v[144:147], v56, s[24:25]
	s_cmp_lt_u32 s12, 0x400
	s_cselect_b32 s24, s98, s100
	s_cselect_b32 s25, s99, s101
	s_lshl_b32 s12, s12, 11
	s_add_u32 s24, s24, s12
	s_addc_u32 s25, s25, 0
	global_load_dwordx4 v[148:151], v56, s[24:25]
	s_cmp_lt_u32 s13, 0x400
	s_cselect_b32 s24, s98, s100
	s_cselect_b32 s25, s99, s101
	s_lshl_b32 s13, s13, 11
	s_add_u32 s24, s24, s13
	s_addc_u32 s25, s25, 0
	global_load_dwordx4 v[152:155], v56, s[24:25]
	s_cmp_lt_u32 s14, 0x400
	s_cselect_b32 s24, s98, s100
	s_cselect_b32 s25, s99, s101
	s_lshl_b32 s14, s14, 11
	s_add_u32 s24, s24, s14
	s_addc_u32 s25, s25, 0
	global_load_dwordx4 v[156:159], v56, s[24:25]
	s_cmp_lt_u32 s15, 0x400
	s_cselect_b32 s24, s98, s100
	s_cselect_b32 s25, s99, s101
	s_lshl_b32 s15, s15, 11
	s_add_u32 s24, s24, s15
	s_addc_u32 s25, s25, 0
	global_load_dwordx4 v[160:163], v56, s[24:25]
	s_cmp_lt_u32 s16, 0x400
	s_cselect_b32 s24, s98, s100
	s_cselect_b32 s25, s99, s101
	s_lshl_b32 s16, s16, 11
	s_add_u32 s24, s24, s16
	s_addc_u32 s25, s25, 0
	global_load_dwordx4 v[164:167], v56, s[24:25]
	s_cmp_lt_u32 s17, 0x400
	s_cselect_b32 s24, s98, s100
	s_cselect_b32 s25, s99, s101
	s_lshl_b32 s17, s17, 11
	s_add_u32 s24, s24, s17
	s_addc_u32 s25, s25, 0
	global_load_dwordx4 v[168:171], v56, s[24:25]
	s_cmp_lt_u32 s18, 0x400
	s_cselect_b32 s24, s98, s100
	s_cselect_b32 s25, s99, s101
	s_lshl_b32 s18, s18, 11
	s_add_u32 s24, s24, s18
	s_addc_u32 s25, s25, 0
	global_load_dwordx4 v[172:175], v56, s[24:25]
	s_cmp_lt_u32 s19, 0x400
	s_cselect_b32 s24, s98, s100
	s_cselect_b32 s25, s99, s101
	s_lshl_b32 s19, s19, 11
	s_add_u32 s24, s24, s19
	s_addc_u32 s25, s25, 0
	global_load_dwordx4 v[176:179], v56, s[24:25]
	s_cmp_lt_u32 s20, 0x400
	s_cselect_b32 s24, s98, s100
	s_cselect_b32 s25, s99, s101
	s_lshl_b32 s20, s20, 11
	s_add_u32 s24, s24, s20
	s_addc_u32 s25, s25, 0
	global_load_dwordx4 v[180:183], v56, s[24:25]
	s_cmp_lt_u32 s21, 0x400
	s_cselect_b32 s24, s98, s100
	s_cselect_b32 s25, s99, s101
	s_lshl_b32 s21, s21, 11
; __device__ __forceinline__ void attn_phase(const Args& a, unsigned char* lds, int lane, int wave) {
;     ...
;         for (int j = 0; j < nsel; j += 8) {
;             const u32x4 ida = *(const u32x4*)(sel + j), idb = *(const u32x4*)(sel + j + 4);
;             u32x4 kk[8], vv[8];
; #pragma unroll
;             for (int i = 0; i < 8; ++i) { const int idx = (int)(i < 4 ? ida[i & 3] : idb[i & 3]); const unsigned char* kp;
;                 if (!sample) kp = KV8 + (size_t)idx * 2048;
;                 else if (idx < 1024) kp = CKV8 + (size_t)(bb * 1024 + idx) * 2048;
;                 else kp = KV8 + (size_t)(TP + bb * 64 + idx - 1024) * 2048;
;                 kk[i] = *(const u32x4*)(kp + lane * 16); vv[i] = *(const u32x4*)(kp + 1024 + lane * 16); }
;             float s[8];
; #pragma unroll
;             for (int i = 0; i < 8; ++i) { float kf[16]; unpack16_fp8(kk[i], kf); float d0 = 0.f, d1 = 0.f;
; #pragma unroll
;                 for (int x = 0; x < 16; x += 2) { d0 += q[x] * kf[x]; d1 += q[x + 1] * kf[x + 1]; }
;                 float d = d0 + d1;
;                 d += __shfl_xor(d, 1); d += __shfl_xor(d, 2); d += __shfl_xor(d, 4); s[i] = d; }
	s_add_u32 s24, s24, s21
	s_addc_u32 s25, s25, 0
	global_load_dwordx4 v[184:187], v56, s[24:25]
	s_cmp_lt_u32 s22, 0x400
	s_cselect_b32 s24, s98, s100
	s_cselect_b32 s25, s99, s101
	s_lshl_b32 s22, s22, 11
	s_add_u32 s24, s24, s22
	s_addc_u32 s25, s25, 0
	global_load_dwordx4 v[188:191], v56, s[24:25]
	s_cmp_lt_u32 s23, 0x400
	s_cselect_b32 s24, s98, s100
	s_cselect_b32 s25, s99, s101
	s_lshl_b32 s23, s23, 11
	s_add_u32 s24, s24, s23
	s_addc_u32 s25, s25, 0
	global_load_dwordx4 v[192:195], v56, s[24:25]
	s_cmp_lt_u32 s8, 0x200000
	s_cselect_b32 s24, s98, s100
	s_cselect_b32 s25, s99, s101
	s_add_u32 s24, s24, s8
	s_addc_u32 s25, s25, 0
	global_load_dwordx4 v[0:3], v56, s[24:25] offset:1024
	s_cmp_lt_u32 s9, 0x200000
	s_cselect_b32 s24, s98, s100
	s_cselect_b32 s25, s99, s101
	s_add_u32 s24, s24, s9
	s_addc_u32 s25, s25, 0
	global_load_dwordx4 v[4:7], v56, s[24:25] offset:1024
	s_cmp_lt_u32 s10, 0x200000
	s_cselect_b32 s24, s98, s100
	s_cselect_b32 s25, s99, s101
	s_add_u32 s24, s24, s10
	s_addc_u32 s25, s25, 0
	global_load_dwordx4 v[8:11], v56, s[24:25] offset:1024
	s_cmp_lt_u32 s11, 0x200000
	s_cselect_b32 s24, s98, s100
	s_cselect_b32 s25, s99, s101
	s_add_u32 s24, s24, s11
	s_addc_u32 s25, s25, 0
	global_load_dwordx4 v[12:15], v56, s[24:25] offset:1024
	s_cmp_lt_u32 s12, 0x200000
	s_cselect_b32 s24, s98, s100
	s_cselect_b32 s25, s99, s101
	s_add_u32 s24, s24, s12
	s_addc_u32 s25, s25, 0
	global_load_dwordx4 v[16:19], v56, s[24:25] offset:1024
	s_cmp_lt_u32 s13, 0x200000
	s_cselect_b32 s24, s98, s100
	s_cselect_b32 s25, s99, s101
	s_add_u32 s24, s24, s13
	s_addc_u32 s25, s25, 0
	global_load_dwordx4 v[20:23], v56, s[24:25] offset:1024
	s_cmp_lt_u32 s14, 0x200000
	s_cselect_b32 s24, s98, s100
	s_cselect_b32 s25, s99, s101
	s_add_u32 s24, s24, s14
	s_addc_u32 s25, s25, 0
	global_load_dwordx4 v[24:27], v56, s[24:25] offset:1024
	s_cmp_lt_u32 s15, 0x200000
	s_cselect_b32 s24, s98, s100
	s_cselect_b32 s25, s99, s101
	s_add_u32 s24, s24, s15
	s_addc_u32 s25, s25, 0
	global_load_dwordx4 v[28:31], v56, s[24:25] offset:1024
	s_cmp_lt_u32 s16, 0x200000
	s_cselect_b32 s24, s98, s100
	s_cselect_b32 s25, s99, s101
	s_add_u32 s24, s24, s16
	s_addc_u32 s25, s25, 0
	global_load_dwordx4 v[32:35], v56, s[24:25] offset:1024
	s_cmp_lt_u32 s17, 0x200000
	s_cselect_b32 s24, s98, s100
	s_cselect_b32 s25, s99, s101
	s_add_u32 s24, s24, s17
	s_addc_u32 s25, s25, 0
	global_load_dwordx4 v[36:39], v56, s[24:25] offset:1024
	s_cmp_lt_u32 s18, 0x200000
	s_cselect_b32 s24, s98, s100
	s_cselect_b32 s25, s99, s101
	s_add_u32 s24, s24, s18
	s_addc_u32 s25, s25, 0
	global_load_dwordx4 v[40:43], v56, s[24:25] offset:1024
	s_cmp_lt_u32 s19, 0x200000
	s_cselect_b32 s24, s98, s100
	s_cselect_b32 s25, s99, s101
	s_add_u32 s24, s24, s19
	s_addc_u32 s25, s25, 0
	global_load_dwordx4 v[44:47], v56, s[24:25] offset:1024
	s_cmp_lt_u32 s20, 0x200000
	s_cselect_b32 s24, s98, s100
	s_cselect_b32 s25, s99, s101
	s_add_u32 s24, s24, s20
	s_addc_u32 s25, s25, 0
	global_load_dwordx4 v[48:51], v56, s[24:25] offset:1024
	s_cmp_lt_u32 s21, 0x200000
	s_cselect_b32 s24, s98, s100
	s_cselect_b32 s25, s99, s101
	s_add_u32 s24, s24, s21
	s_addc_u32 s25, s25, 0
	global_load_dwordx4 v[52:55], v56, s[24:25] offset:1024
	s_cmp_lt_u32 s22, 0x200000
	s_cselect_b32 s24, s98, s100
	s_cselect_b32 s25, s99, s101
	s_add_u32 s24, s24, s22
	s_addc_u32 s25, s25, 0
	global_load_dwordx4 v[196:199], v56, s[24:25] offset:1024
	s_cmp_lt_u32 s23, 0x200000
	s_cselect_b32 s24, s98, s100
	s_cselect_b32 s25, s99, s101
	s_add_u32 s24, s24, s23
	s_addc_u32 s25, s25, 0
	global_load_dwordx4 v[200:203], v56, s[24:25] offset:1024
	s_add_i32 s3, s3, -1
.Lat_blk:
	s_waitcnt vmcnt(30)
	v_cvt_pk_f32_fp8_e32 v[204:205], v132
	v_cvt_pk_f32_fp8_e32 v[206:207], v136
	v_pk_mul_f32 v[220:221], v[204:205], v[78:79]
	v_pk_mul_f32 v[222:223], v[206:207], v[78:79]
	v_cvt_pk_f32_fp8_sdwa v[208:209], v132 src0_sel:WORD_1
	v_cvt_pk_f32_fp8_sdwa v[210:211], v136 src0_sel:WORD_1
	v_pk_fma_f32 v[220:221], v[208:209], v[80:81], v[220:221]
	v_pk_fma_f32 v[222:223], v[210:211], v[80:81], v[222:223]
	v_cvt_pk_f32_fp8_e32 v[212:213], v133
	v_cvt_pk_f32_fp8_e32 v[214:215], v137
	v_pk_fma_f32 v[220:221], v[212:213], v[82:83], v[220:221]
	v_pk_fma_f32 v[222:223], v[214:215], v[82:83], v[222:223]
	v_cvt_pk_f32_fp8_sdwa v[216:217], v133 src0_sel:WORD_1
	v_cvt_pk_f32_fp8_sdwa v[218:219], v137 src0_sel:WORD_1
	v_pk_fma_f32 v[220:221], v[216:217], v[84:85], v[220:221]
	v_pk_fma_f32 v[222:223], v[218:219], v[84:85], v[222:223]
	v_cvt_pk_f32_fp8_e32 v[204:205], v134
	v_cvt_pk_f32_fp8_e32 v[206:207], v138
	v_pk_fma_f32 v[220:221], v[204:205], v[86:87], v[220:221]
	v_pk_fma_f32 v[222:223], v[206:207], v[86:87], v[222:223]
	v_cvt_pk_f32_fp8_sdwa v[208:209], v134 src0_sel:WORD_1
	v_cvt_pk_f32_fp8_sdwa v[210:211], v138 src0_sel:WORD_1
	v_pk_fma_f32 v[220:221], v[208:209], v[88:89], v[220:221]
	v_pk_fma_f32 v[222:223], v[210:211], v[88:89], v[222:223]
	v_cvt_pk_f32_fp8_e32 v[212:213], v135
	v_cvt_pk_f32_fp8_e32 v[214:215], v139
	v_pk_fma_f32 v[220:221], v[212:213], v[90:91], v[220:221]
	v_pk_fma_f32 v[222:223], v[214:215], v[90:91], v[222:223]
	v_cvt_pk_f32_fp8_sdwa v[216:217], v135 src0_sel:WORD_1
	v_cvt_pk_f32_fp8_sdwa v[218:219], v139 src0_sel:WORD_1
	v_pk_fma_f32 v[220:221], v[216:217], v[92:93], v[220:221]
	v_pk_fma_f32 v[222:223], v[218:219], v[92:93], v[222:223]
	s_waitcnt vmcnt(28)
; __device__ __forceinline__ void attn_phase(const Args& a, unsigned char* lds, int lane, int wave) {
;     ...
;             float s[8];
; #pragma unroll
;             for (int i = 0; i < 8; ++i) { float kf[16]; unpack16_fp8(kk[i], kf); float d0 = 0.f, d1 = 0.f;
; #pragma unroll
;                 for (int x = 0; x < 16; x += 2) { d0 += q[x] * kf[x]; d1 += q[x + 1] * kf[x + 1]; }
;                 float d = d0 + d1;
;                 d += __shfl_xor(d, 1); d += __shfl_xor(d, 2); d += __shfl_xor(d, 4); s[i] = d; }
	v_cvt_pk_f32_fp8_e32 v[204:205], v140
	v_cvt_pk_f32_fp8_e32 v[206:207], v144
	v_pk_mul_f32 v[224:225], v[204:205], v[78:79]
	v_pk_mul_f32 v[226:227], v[206:207], v[78:79]
	v_cvt_pk_f32_fp8_sdwa v[208:209], v140 src0_sel:WORD_1
	v_cvt_pk_f32_fp8_sdwa v[210:211], v144 src0_sel:WORD_1
	v_pk_fma_f32 v[224:225], v[208:209], v[80:81], v[224:225]
	v_pk_fma_f32 v[226:227], v[210:211], v[80:81], v[226:227]
	v_cvt_pk_f32_fp8_e32 v[212:213], v141
	v_cvt_pk_f32_fp8_e32 v[214:215], v145
	v_pk_fma_f32 v[224:225], v[212:213], v[82:83], v[224:225]
	v_pk_fma_f32 v[226:227], v[214:215], v[82:83], v[226:227]
	v_cvt_pk_f32_fp8_sdwa v[216:217], v141 src0_sel:WORD_1
	v_cvt_pk_f32_fp8_sdwa v[218:219], v145 src0_sel:WORD_1
	v_pk_fma_f32 v[224:225], v[216:217], v[84:85], v[224:225]
	v_pk_fma_f32 v[226:227], v[218:219], v[84:85], v[226:227]
	v_cvt_pk_f32_fp8_e32 v[204:205], v142
	v_cvt_pk_f32_fp8_e32 v[206:207], v146
	v_pk_fma_f32 v[224:225], v[204:205], v[86:87], v[224:225]
	v_pk_fma_f32 v[226:227], v[206:207], v[86:87], v[226:227]
	v_cvt_pk_f32_fp8_sdwa v[208:209], v142 src0_sel:WORD_1
	v_cvt_pk_f32_fp8_sdwa v[210:211], v146 src0_sel:WORD_1
	v_pk_fma_f32 v[224:225], v[208:209], v[88:89], v[224:225]
	v_pk_fma_f32 v[226:227], v[210:211], v[88:89], v[226:227]
	v_cvt_pk_f32_fp8_e32 v[212:213], v143
	v_cvt_pk_f32_fp8_e32 v[214:215], v147
	v_pk_fma_f32 v[224:225], v[212:213], v[90:91], v[224:225]
	v_pk_fma_f32 v[226:227], v[214:215], v[90:91], v[226:227]
	v_cvt_pk_f32_fp8_sdwa v[216:217], v143 src0_sel:WORD_1
	v_cvt_pk_f32_fp8_sdwa v[218:219], v147 src0_sel:WORD_1
	v_pk_fma_f32 v[224:225], v[216:217], v[92:93], v[224:225]
	v_pk_fma_f32 v[226:227], v[218:219], v[92:93], v[226:227]
	v_add_f32_e32 v110, v220, v221
	v_add_f32_e32 v111, v222, v223
	v_add_f32_e32 v112, v224, v225
	v_add_f32_e32 v113, v226, v227
	v_add_f32_dpp v110, v110, v110 quad_perm:[1,0,3,2] row_mask:0xf bank_mask:0xf
	v_add_f32_dpp v111, v111, v111 quad_perm:[1,0,3,2] row_mask:0xf bank_mask:0xf
	v_add_f32_dpp v112, v112, v112 quad_perm:[1,0,3,2] row_mask:0xf bank_mask:0xf
	v_add_f32_dpp v113, v113, v113 quad_perm:[1,0,3,2] row_mask:0xf bank_mask:0xf
	v_add_f32_dpp v110, v110, v110 quad_perm:[2,3,0,1] row_mask:0xf bank_mask:0xf
	v_add_f32_dpp v111, v111, v111 quad_perm:[2,3,0,1] row_mask:0xf bank_mask:0xf
	v_add_f32_dpp v112, v112, v112 quad_perm:[2,3,0,1] row_mask:0xf bank_mask:0xf
	v_add_f32_dpp v113, v113, v113 quad_perm:[2,3,0,1] row_mask:0xf bank_mask:0xf
	v_add_f32_dpp v110, v110, v110 row_half_mirror row_mask:0xf bank_mask:0xf
	v_add_f32_dpp v111, v111, v111 row_half_mirror row_mask:0xf bank_mask:0xf
	v_add_f32_dpp v112, v112, v112 row_half_mirror row_mask:0xf bank_mask:0xf
	v_add_f32_dpp v113, v113, v113 row_half_mirror row_mask:0xf bank_mask:0xf
	s_waitcnt vmcnt(26)
	v_cvt_pk_f32_fp8_e32 v[204:205], v148
	v_cvt_pk_f32_fp8_e32 v[206:207], v152
	v_pk_mul_f32 v[220:221], v[204:205], v[78:79]
	v_pk_mul_f32 v[222:223], v[206:207], v[78:79]
	v_cvt_pk_f32_fp8_sdwa v[208:209], v148 src0_sel:WORD_1
	v_cvt_pk_f32_fp8_sdwa v[210:211], v152 src0_sel:WORD_1
	v_pk_fma_f32 v[220:221], v[208:209], v[80:81], v[220:221]
	v_pk_fma_f32 v[222:223], v[210:211], v[80:81], v[222:223]
	v_cvt_pk_f32_fp8_e32 v[212:213], v149
	v_cvt_pk_f32_fp8_e32 v[214:215], v153
	v_pk_fma_f32 v[220:221], v[212:213], v[82:83], v[220:221]
	v_pk_fma_f32 v[222:223], v[214:215], v[82:83], v[222:223]
	v_cvt_pk_f32_fp8_sdwa v[216:217], v149 src0_sel:WORD_1
	v_cvt_pk_f32_fp8_sdwa v[218:219], v153 src0_sel:WORD_1
	v_pk_fma_f32 v[220:221], v[216:217], v[84:85], v[220:221]
	v_pk_fma_f32 v[222:223], v[218:219], v[84:85], v[222:223]
	v_cvt_pk_f32_fp8_e32 v[204:205], v150
	v_cvt_pk_f32_fp8_e32 v[206:207], v154
	v_pk_fma_f32 v[220:221], v[204:205], v[86:87], v[220:221]
	v_pk_fma_f32 v[222:223], v[206:207], v[86:87], v[222:223]
	v_cvt_pk_f32_fp8_sdwa v[208:209], v150 src0_sel:WORD_1
	v_cvt_pk_f32_fp8_sdwa v[210:211], v154 src0_sel:WORD_1
	v_pk_fma_f32 v[220:221], v[208:209], v[88:89], v[220:221]
	v_pk_fma_f32 v[222:223], v[210:211], v[88:89], v[222:223]
	v_cvt_pk_f32_fp8_e32 v[212:213], v151
	v_cvt_pk_f32_fp8_e32 v[214:215], v155
	v_pk_fma_f32 v[220:221], v[212:213], v[90:91], v[220:221]
	v_pk_fma_f32 v[222:223], v[214:215], v[90:91], v[222:223]
	v_cvt_pk_f32_fp8_sdwa v[216:217], v151 src0_sel:WORD_1
	v_cvt_pk_f32_fp8_sdwa v[218:219], v155 src0_sel:WORD_1
	v_pk_fma_f32 v[220:221], v[216:217], v[92:93], v[220:221]
	v_pk_fma_f32 v[222:223], v[218:219], v[92:93], v[222:223]
	s_waitcnt vmcnt(24)
; __device__ __forceinline__ void attn_phase(const Args& a, unsigned char* lds, int lane, int wave) {
;     ...
;             float s[8];
; #pragma unroll
;             for (int i = 0; i < 8; ++i) { float kf[16]; unpack16_fp8(kk[i], kf); float d0 = 0.f, d1 = 0.f;
; #pragma unroll
;                 for (int x = 0; x < 16; x += 2) { d0 += q[x] * kf[x]; d1 += q[x + 1] * kf[x + 1]; }
;                 float d = d0 + d1;
;                 d += __shfl_xor(d, 1); d += __shfl_xor(d, 2); d += __shfl_xor(d, 4); s[i] = d; }
	v_cvt_pk_f32_fp8_e32 v[204:205], v156
	v_cvt_pk_f32_fp8_e32 v[206:207], v160
	v_pk_mul_f32 v[224:225], v[204:205], v[78:79]
	v_pk_mul_f32 v[226:227], v[206:207], v[78:79]
	v_cvt_pk_f32_fp8_sdwa v[208:209], v156 src0_sel:WORD_1
	v_cvt_pk_f32_fp8_sdwa v[210:211], v160 src0_sel:WORD_1
	v_pk_fma_f32 v[224:225], v[208:209], v[80:81], v[224:225]
	v_pk_fma_f32 v[226:227], v[210:211], v[80:81], v[226:227]
	v_cvt_pk_f32_fp8_e32 v[212:213], v157
	v_cvt_pk_f32_fp8_e32 v[214:215], v161
	v_pk_fma_f32 v[224:225], v[212:213], v[82:83], v[224:225]
	v_pk_fma_f32 v[226:227], v[214:215], v[82:83], v[226:227]
	v_cvt_pk_f32_fp8_sdwa v[216:217], v157 src0_sel:WORD_1
	v_cvt_pk_f32_fp8_sdwa v[218:219], v161 src0_sel:WORD_1
	v_pk_fma_f32 v[224:225], v[216:217], v[84:85], v[224:225]
	v_pk_fma_f32 v[226:227], v[218:219], v[84:85], v[226:227]
	v_cvt_pk_f32_fp8_e32 v[204:205], v158
	v_cvt_pk_f32_fp8_e32 v[206:207], v162
	v_pk_fma_f32 v[224:225], v[204:205], v[86:87], v[224:225]
	v_pk_fma_f32 v[226:227], v[206:207], v[86:87], v[226:227]
	v_cvt_pk_f32_fp8_sdwa v[208:209], v158 src0_sel:WORD_1
	v_cvt_pk_f32_fp8_sdwa v[210:211], v162 src0_sel:WORD_1
	v_pk_fma_f32 v[224:225], v[208:209], v[88:89], v[224:225]
	v_pk_fma_f32 v[226:227], v[210:211], v[88:89], v[226:227]
	v_cvt_pk_f32_fp8_e32 v[212:213], v159
	v_cvt_pk_f32_fp8_e32 v[214:215], v163
	v_pk_fma_f32 v[224:225], v[212:213], v[90:91], v[224:225]
	v_pk_fma_f32 v[226:227], v[214:215], v[90:91], v[226:227]
	v_cvt_pk_f32_fp8_sdwa v[216:217], v159 src0_sel:WORD_1
	v_cvt_pk_f32_fp8_sdwa v[218:219], v163 src0_sel:WORD_1
	v_pk_fma_f32 v[224:225], v[216:217], v[92:93], v[224:225]
	v_pk_fma_f32 v[226:227], v[218:219], v[92:93], v[226:227]
	v_add_f32_e32 v114, v220, v221
	v_add_f32_e32 v115, v222, v223
	v_add_f32_e32 v116, v224, v225
	v_add_f32_e32 v117, v226, v227
	v_add_f32_dpp v114, v114, v114 quad_perm:[1,0,3,2] row_mask:0xf bank_mask:0xf
	v_add_f32_dpp v115, v115, v115 quad_perm:[1,0,3,2] row_mask:0xf bank_mask:0xf
	v_add_f32_dpp v116, v116, v116 quad_perm:[1,0,3,2] row_mask:0xf bank_mask:0xf
	v_add_f32_dpp v117, v117, v117 quad_perm:[1,0,3,2] row_mask:0xf bank_mask:0xf
	v_add_f32_dpp v114, v114, v114 quad_perm:[2,3,0,1] row_mask:0xf bank_mask:0xf
	v_add_f32_dpp v115, v115, v115 quad_perm:[2,3,0,1] row_mask:0xf bank_mask:0xf
	v_add_f32_dpp v116, v116, v116 quad_perm:[2,3,0,1] row_mask:0xf bank_mask:0xf
	v_add_f32_dpp v117, v117, v117 quad_perm:[2,3,0,1] row_mask:0xf bank_mask:0xf
	v_add_f32_dpp v114, v114, v114 row_half_mirror row_mask:0xf bank_mask:0xf
	v_add_f32_dpp v115, v115, v115 row_half_mirror row_mask:0xf bank_mask:0xf
	v_add_f32_dpp v116, v116, v116 row_half_mirror row_mask:0xf bank_mask:0xf
	v_add_f32_dpp v117, v117, v117 row_half_mirror row_mask:0xf bank_mask:0xf
	s_waitcnt vmcnt(22)
	v_cvt_pk_f32_fp8_e32 v[204:205], v164
	v_cvt_pk_f32_fp8_e32 v[206:207], v168
	v_pk_mul_f32 v[220:221], v[204:205], v[78:79]
	v_pk_mul_f32 v[222:223], v[206:207], v[78:79]
	v_cvt_pk_f32_fp8_sdwa v[208:209], v164 src0_sel:WORD_1
	v_cvt_pk_f32_fp8_sdwa v[210:211], v168 src0_sel:WORD_1
	v_pk_fma_f32 v[220:221], v[208:209], v[80:81], v[220:221]
	v_pk_fma_f32 v[222:223], v[210:211], v[80:81], v[222:223]
	v_cvt_pk_f32_fp8_e32 v[212:213], v165
	v_cvt_pk_f32_fp8_e32 v[214:215], v169
	v_pk_fma_f32 v[220:221], v[212:213], v[82:83], v[220:221]
	v_pk_fma_f32 v[222:223], v[214:215], v[82:83], v[222:223]
	v_cvt_pk_f32_fp8_sdwa v[216:217], v165 src0_sel:WORD_1
	v_cvt_pk_f32_fp8_sdwa v[218:219], v169 src0_sel:WORD_1
	v_pk_fma_f32 v[220:221], v[216:217], v[84:85], v[220:221]
	v_pk_fma_f32 v[222:223], v[218:219], v[84:85], v[222:223]
	v_cvt_pk_f32_fp8_e32 v[204:205], v166
	v_cvt_pk_f32_fp8_e32 v[206:207], v170
	v_pk_fma_f32 v[220:221], v[204:205], v[86:87], v[220:221]
	v_pk_fma_f32 v[222:223], v[206:207], v[86:87], v[222:223]
	v_cvt_pk_f32_fp8_sdwa v[208:209], v166 src0_sel:WORD_1
	v_cvt_pk_f32_fp8_sdwa v[210:211], v170 src0_sel:WORD_1
	v_pk_fma_f32 v[220:221], v[208:209], v[88:89], v[220:221]
	v_pk_fma_f32 v[222:223], v[210:211], v[88:89], v[222:223]
	v_cvt_pk_f32_fp8_e32 v[212:213], v167
	v_cvt_pk_f32_fp8_e32 v[214:215], v171
	v_pk_fma_f32 v[220:221], v[212:213], v[90:91], v[220:221]
	v_pk_fma_f32 v[222:223], v[214:215], v[90:91], v[222:223]
	v_cvt_pk_f32_fp8_sdwa v[216:217], v167 src0_sel:WORD_1
	v_cvt_pk_f32_fp8_sdwa v[218:219], v171 src0_sel:WORD_1
	v_pk_fma_f32 v[220:221], v[216:217], v[92:93], v[220:221]
	v_pk_fma_f32 v[222:223], v[218:219], v[92:93], v[222:223]
	s_waitcnt vmcnt(20)
; __device__ __forceinline__ void attn_phase(const Args& a, unsigned char* lds, int lane, int wave) {
;     ...
;             float s[8];
; #pragma unroll
;             for (int i = 0; i < 8; ++i) { float kf[16]; unpack16_fp8(kk[i], kf); float d0 = 0.f, d1 = 0.f;
; #pragma unroll
;                 for (int x = 0; x < 16; x += 2) { d0 += q[x] * kf[x]; d1 += q[x + 1] * kf[x + 1]; }
;                 float d = d0 + d1;
;                 d += __shfl_xor(d, 1); d += __shfl_xor(d, 2); d += __shfl_xor(d, 4); s[i] = d; }
	v_cvt_pk_f32_fp8_e32 v[204:205], v172
	v_cvt_pk_f32_fp8_e32 v[206:207], v176
	v_pk_mul_f32 v[224:225], v[204:205], v[78:79]
	v_pk_mul_f32 v[226:227], v[206:207], v[78:79]
	v_cvt_pk_f32_fp8_sdwa v[208:209], v172 src0_sel:WORD_1
	v_cvt_pk_f32_fp8_sdwa v[210:211], v176 src0_sel:WORD_1
	v_pk_fma_f32 v[224:225], v[208:209], v[80:81], v[224:225]
	v_pk_fma_f32 v[226:227], v[210:211], v[80:81], v[226:227]
	v_cvt_pk_f32_fp8_e32 v[212:213], v173
	v_cvt_pk_f32_fp8_e32 v[214:215], v177
	v_pk_fma_f32 v[224:225], v[212:213], v[82:83], v[224:225]
	v_pk_fma_f32 v[226:227], v[214:215], v[82:83], v[226:227]
	v_cvt_pk_f32_fp8_sdwa v[216:217], v173 src0_sel:WORD_1
	v_cvt_pk_f32_fp8_sdwa v[218:219], v177 src0_sel:WORD_1
	v_pk_fma_f32 v[224:225], v[216:217], v[84:85], v[224:225]
	v_pk_fma_f32 v[226:227], v[218:219], v[84:85], v[226:227]
	v_cvt_pk_f32_fp8_e32 v[204:205], v174
	v_cvt_pk_f32_fp8_e32 v[206:207], v178
	v_pk_fma_f32 v[224:225], v[204:205], v[86:87], v[224:225]
	v_pk_fma_f32 v[226:227], v[206:207], v[86:87], v[226:227]
	v_cvt_pk_f32_fp8_sdwa v[208:209], v174 src0_sel:WORD_1
	v_cvt_pk_f32_fp8_sdwa v[210:211], v178 src0_sel:WORD_1
	v_pk_fma_f32 v[224:225], v[208:209], v[88:89], v[224:225]
	v_pk_fma_f32 v[226:227], v[210:211], v[88:89], v[226:227]
	v_cvt_pk_f32_fp8_e32 v[212:213], v175
	v_cvt_pk_f32_fp8_e32 v[214:215], v179
	v_pk_fma_f32 v[224:225], v[212:213], v[90:91], v[224:225]
	v_pk_fma_f32 v[226:227], v[214:215], v[90:91], v[226:227]
	v_cvt_pk_f32_fp8_sdwa v[216:217], v175 src0_sel:WORD_1
	v_cvt_pk_f32_fp8_sdwa v[218:219], v179 src0_sel:WORD_1
	v_pk_fma_f32 v[224:225], v[216:217], v[92:93], v[224:225]
	v_pk_fma_f32 v[226:227], v[218:219], v[92:93], v[226:227]
	v_add_f32_e32 v118, v220, v221
	v_add_f32_e32 v119, v222, v223
	v_add_f32_e32 v120, v224, v225
	v_add_f32_e32 v121, v226, v227
	v_add_f32_dpp v118, v118, v118 quad_perm:[1,0,3,2] row_mask:0xf bank_mask:0xf
	v_add_f32_dpp v119, v119, v119 quad_perm:[1,0,3,2] row_mask:0xf bank_mask:0xf
	v_add_f32_dpp v120, v120, v120 quad_perm:[1,0,3,2] row_mask:0xf bank_mask:0xf
	v_add_f32_dpp v121, v121, v121 quad_perm:[1,0,3,2] row_mask:0xf bank_mask:0xf
	v_add_f32_dpp v118, v118, v118 quad_perm:[2,3,0,1] row_mask:0xf bank_mask:0xf
	v_add_f32_dpp v119, v119, v119 quad_perm:[2,3,0,1] row_mask:0xf bank_mask:0xf
	v_add_f32_dpp v120, v120, v120 quad_perm:[2,3,0,1] row_mask:0xf bank_mask:0xf
	v_add_f32_dpp v121, v121, v121 quad_perm:[2,3,0,1] row_mask:0xf bank_mask:0xf
	v_add_f32_dpp v118, v118, v118 row_half_mirror row_mask:0xf bank_mask:0xf
	v_add_f32_dpp v119, v119, v119 row_half_mirror row_mask:0xf bank_mask:0xf
	v_add_f32_dpp v120, v120, v120 row_half_mirror row_mask:0xf bank_mask:0xf
	v_add_f32_dpp v121, v121, v121 row_half_mirror row_mask:0xf bank_mask:0xf
	s_waitcnt vmcnt(18)
	v_cvt_pk_f32_fp8_e32 v[204:205], v180
	v_cvt_pk_f32_fp8_e32 v[206:207], v184
	v_pk_mul_f32 v[220:221], v[204:205], v[78:79]
	v_pk_mul_f32 v[222:223], v[206:207], v[78:79]
	v_cvt_pk_f32_fp8_sdwa v[208:209], v180 src0_sel:WORD_1
	v_cvt_pk_f32_fp8_sdwa v[210:211], v184 src0_sel:WORD_1
	v_pk_fma_f32 v[220:221], v[208:209], v[80:81], v[220:221]
	v_pk_fma_f32 v[222:223], v[210:211], v[80:81], v[222:223]
	v_cvt_pk_f32_fp8_e32 v[212:213], v181
	v_cvt_pk_f32_fp8_e32 v[214:215], v185
	v_pk_fma_f32 v[220:221], v[212:213], v[82:83], v[220:221]
	v_pk_fma_f32 v[222:223], v[214:215], v[82:83], v[222:223]
	v_cvt_pk_f32_fp8_sdwa v[216:217], v181 src0_sel:WORD_1
	v_cvt_pk_f32_fp8_sdwa v[218:219], v185 src0_sel:WORD_1
	v_pk_fma_f32 v[220:221], v[216:217], v[84:85], v[220:221]
	v_pk_fma_f32 v[222:223], v[218:219], v[84:85], v[222:223]
	v_cvt_pk_f32_fp8_e32 v[204:205], v182
	v_cvt_pk_f32_fp8_e32 v[206:207], v186
	v_pk_fma_f32 v[220:221], v[204:205], v[86:87], v[220:221]
	v_pk_fma_f32 v[222:223], v[206:207], v[86:87], v[222:223]
	v_cvt_pk_f32_fp8_sdwa v[208:209], v182 src0_sel:WORD_1
	v_cvt_pk_f32_fp8_sdwa v[210:211], v186 src0_sel:WORD_1
	v_pk_fma_f32 v[220:221], v[208:209], v[88:89], v[220:221]
	v_pk_fma_f32 v[222:223], v[210:211], v[88:89], v[222:223]
	v_cvt_pk_f32_fp8_e32 v[212:213], v183
	v_cvt_pk_f32_fp8_e32 v[214:215], v187
	v_pk_fma_f32 v[220:221], v[212:213], v[90:91], v[220:221]
	v_pk_fma_f32 v[222:223], v[214:215], v[90:91], v[222:223]
	v_cvt_pk_f32_fp8_sdwa v[216:217], v183 src0_sel:WORD_1
	v_cvt_pk_f32_fp8_sdwa v[218:219], v187 src0_sel:WORD_1
	v_pk_fma_f32 v[220:221], v[216:217], v[92:93], v[220:221]
	v_pk_fma_f32 v[222:223], v[218:219], v[92:93], v[222:223]
	s_waitcnt vmcnt(16)
; __device__ __forceinline__ void attn_phase(const Args& a, unsigned char* lds, int lane, int wave) {
;     ...
;             for (int i = 0; i < 8; ++i) { float kf[16]; unpack16_fp8(kk[i], kf); float d0 = 0.f, d1 = 0.f;
; #pragma unroll
;                 for (int x = 0; x < 16; x += 2) { d0 += q[x] * kf[x]; d1 += q[x + 1] * kf[x + 1]; }
;                 float d = d0 + d1;
;                 d += __shfl_xor(d, 1); d += __shfl_xor(d, 2); d += __shfl_xor(d, 4); s[i] = d; }
;             const float mn = fmaxf(fmaxf(fmaxf(mx, fmaxf(s[0], s[1])), fmaxf(s[2], s[3])), fmaxf(fmaxf(s[4], s[5]), fmaxf(s[6], s[7])));
;             const float al = __builtin_amdgcn_exp2f(mx - mn);
;             float p[8];
; #pragma unroll
;             for (int i = 0; i < 8; ++i) p[i] = __builtin_amdgcn_exp2f(s[i] - mn);
;             l = l * al + ((p[0] + p[1]) + (p[2] + p[3])) + ((p[4] + p[5]) + (p[6] + p[7]));
; #pragma unroll
;             for (int d = 0; d < 16; ++d) o[d] *= al;
	v_cvt_pk_f32_fp8_e32 v[204:205], v188
	v_cvt_pk_f32_fp8_e32 v[206:207], v192
	v_pk_mul_f32 v[224:225], v[204:205], v[78:79]
	v_pk_mul_f32 v[226:227], v[206:207], v[78:79]
	v_cvt_pk_f32_fp8_sdwa v[208:209], v188 src0_sel:WORD_1
	v_cvt_pk_f32_fp8_sdwa v[210:211], v192 src0_sel:WORD_1
	v_pk_fma_f32 v[224:225], v[208:209], v[80:81], v[224:225]
	v_pk_fma_f32 v[226:227], v[210:211], v[80:81], v[226:227]
	v_cvt_pk_f32_fp8_e32 v[212:213], v189
	v_cvt_pk_f32_fp8_e32 v[214:215], v193
	v_pk_fma_f32 v[224:225], v[212:213], v[82:83], v[224:225]
	v_pk_fma_f32 v[226:227], v[214:215], v[82:83], v[226:227]
	v_cvt_pk_f32_fp8_sdwa v[216:217], v189 src0_sel:WORD_1
	v_cvt_pk_f32_fp8_sdwa v[218:219], v193 src0_sel:WORD_1
	v_pk_fma_f32 v[224:225], v[216:217], v[84:85], v[224:225]
	v_pk_fma_f32 v[226:227], v[218:219], v[84:85], v[226:227]
	v_cvt_pk_f32_fp8_e32 v[204:205], v190
	v_cvt_pk_f32_fp8_e32 v[206:207], v194
	v_pk_fma_f32 v[224:225], v[204:205], v[86:87], v[224:225]
	v_pk_fma_f32 v[226:227], v[206:207], v[86:87], v[226:227]
	v_cvt_pk_f32_fp8_sdwa v[208:209], v190 src0_sel:WORD_1
	v_cvt_pk_f32_fp8_sdwa v[210:211], v194 src0_sel:WORD_1
	v_pk_fma_f32 v[224:225], v[208:209], v[88:89], v[224:225]
	v_pk_fma_f32 v[226:227], v[210:211], v[88:89], v[226:227]
	v_cvt_pk_f32_fp8_e32 v[212:213], v191
	v_cvt_pk_f32_fp8_e32 v[214:215], v195
	v_pk_fma_f32 v[224:225], v[212:213], v[90:91], v[224:225]
	v_pk_fma_f32 v[226:227], v[214:215], v[90:91], v[226:227]
	v_cvt_pk_f32_fp8_sdwa v[216:217], v191 src0_sel:WORD_1
	v_cvt_pk_f32_fp8_sdwa v[218:219], v195 src0_sel:WORD_1
	v_pk_fma_f32 v[224:225], v[216:217], v[92:93], v[224:225]
	v_pk_fma_f32 v[226:227], v[218:219], v[92:93], v[226:227]
	v_add_f32_e32 v122, v220, v221
	v_add_f32_e32 v123, v222, v223
	v_add_f32_e32 v124, v224, v225
	v_add_f32_e32 v125, v226, v227
	v_add_f32_dpp v122, v122, v122 quad_perm:[1,0,3,2] row_mask:0xf bank_mask:0xf
	v_add_f32_dpp v123, v123, v123 quad_perm:[1,0,3,2] row_mask:0xf bank_mask:0xf
	v_add_f32_dpp v124, v124, v124 quad_perm:[1,0,3,2] row_mask:0xf bank_mask:0xf
	v_add_f32_dpp v125, v125, v125 quad_perm:[1,0,3,2] row_mask:0xf bank_mask:0xf
	v_add_f32_dpp v122, v122, v122 quad_perm:[2,3,0,1] row_mask:0xf bank_mask:0xf
	v_add_f32_dpp v123, v123, v123 quad_perm:[2,3,0,1] row_mask:0xf bank_mask:0xf
	v_add_f32_dpp v124, v124, v124 quad_perm:[2,3,0,1] row_mask:0xf bank_mask:0xf
	v_add_f32_dpp v125, v125, v125 quad_perm:[2,3,0,1] row_mask:0xf bank_mask:0xf
	v_add_f32_dpp v122, v122, v122 row_half_mirror row_mask:0xf bank_mask:0xf
	v_add_f32_dpp v123, v123, v123 row_half_mirror row_mask:0xf bank_mask:0xf
	v_add_f32_dpp v124, v124, v124 row_half_mirror row_mask:0xf bank_mask:0xf
	v_add_f32_dpp v125, v125, v125 row_half_mirror row_mask:0xf bank_mask:0xf
	v_max3_f32 v228, v110, v111, v112
	v_max3_f32 v229, v113, v114, v115
	v_max3_f32 v230, v116, v117, v118
	v_max3_f32 v231, v119, v120, v121
	v_max3_f32 v232, v122, v123, v124
	v_max3_f32 v233, v125, v109, v228
	v_max3_f32 v234, v229, v230, v231
	v_max3_f32 v235, v232, v233, v234
	v_sub_f32_e32 v236, v109, v235
	v_sub_f32_e32 v110, v110, v235
	v_sub_f32_e32 v111, v111, v235
	v_sub_f32_e32 v112, v112, v235
	v_sub_f32_e32 v113, v113, v235
	v_sub_f32_e32 v114, v114, v235
	v_sub_f32_e32 v115, v115, v235
	v_sub_f32_e32 v116, v116, v235
	v_sub_f32_e32 v117, v117, v235
	v_sub_f32_e32 v118, v118, v235
	v_sub_f32_e32 v119, v119, v235
	v_sub_f32_e32 v120, v120, v235
	v_sub_f32_e32 v121, v121, v235
	v_sub_f32_e32 v122, v122, v235
	v_sub_f32_e32 v123, v123, v235
	v_sub_f32_e32 v124, v124, v235
	v_sub_f32_e32 v125, v125, v235
	v_exp_f32_e32 v244, v236
	v_exp_f32_e32 v110, v110
	v_exp_f32_e32 v111, v111
	v_exp_f32_e32 v112, v112
	v_exp_f32_e32 v113, v113
	v_exp_f32_e32 v114, v114
	v_exp_f32_e32 v115, v115
	v_exp_f32_e32 v116, v116
	v_exp_f32_e32 v117, v117
	v_exp_f32_e32 v118, v118
	v_exp_f32_e32 v119, v119
	v_exp_f32_e32 v120, v120
	v_exp_f32_e32 v121, v121
	v_exp_f32_e32 v122, v122
	v_exp_f32_e32 v123, v123
	v_exp_f32_e32 v124, v124
	v_exp_f32_e32 v125, v125
	v_mov_b32_e32 v109, v235
	v_pk_mul_f32 v[62:63], v[62:63], v[244:245] op_sel_hi:[1,0]
	v_pk_mul_f32 v[64:65], v[64:65], v[244:245] op_sel_hi:[1,0]
	v_pk_mul_f32 v[66:67], v[66:67], v[244:245] op_sel_hi:[1,0]
	v_pk_mul_f32 v[68:69], v[68:69], v[244:245] op_sel_hi:[1,0]
	v_pk_mul_f32 v[70:71], v[70:71], v[244:245] op_sel_hi:[1,0]
	v_pk_mul_f32 v[72:73], v[72:73], v[244:245] op_sel_hi:[1,0]
	v_pk_mul_f32 v[74:75], v[74:75], v[244:245] op_sel_hi:[1,0]
	v_pk_mul_f32 v[76:77], v[76:77], v[244:245] op_sel_hi:[1,0]
	v_add_f32_e32 v228, v110, v111
	v_add_f32_e32 v229, v112, v113
	v_add_f32_e32 v230, v114, v115
	v_add_f32_e32 v231, v116, v117
	v_add_f32_e32 v232, v118, v119
	v_add_f32_e32 v233, v120, v121
	v_add_f32_e32 v234, v122, v123
	v_add_f32_e32 v235, v124, v125
	v_add_f32_e32 v228, v228, v229
	v_add_f32_e32 v230, v230, v231
	v_add_f32_e32 v232, v232, v233
	v_add_f32_e32 v234, v234, v235
	v_add_f32_e32 v228, v228, v230
	v_add_f32_e32 v232, v232, v234
	v_add_f32_e32 v228, v228, v232
	v_fma_f32 v108, v108, v244, v228
	s_add_i32 s31, s31, 64
	v_mov_b32_e32 v246, s31
	ds_read_b128 v[204:207], v246
	ds_read_b128 v[208:211], v246 offset:16
	ds_read_b128 v[212:215], v246 offset:32
	ds_read_b128 v[216:219], v246 offset:48
	s_waitcnt lgkmcnt(0)
; __device__ __forceinline__ void attn_phase(const Args& a, unsigned char* lds, int lane, int wave) {
;     ...
;             const u32x4 ida = *(const u32x4*)(sel + j), idb = *(const u32x4*)(sel + j + 4);
;             u32x4 kk[8], vv[8];
; #pragma unroll
;             for (int i = 0; i < 8; ++i) { const int idx = (int)(i < 4 ? ida[i & 3] : idb[i & 3]); const unsigned char* kp;
;                 if (!sample) kp = KV8 + (size_t)idx * 2048;
;                 else if (idx < 1024) kp = CKV8 + (size_t)(bb * 1024 + idx) * 2048;
;                 else kp = KV8 + (size_t)(TP + bb * 64 + idx - 1024) * 2048;
;                 kk[i] = *(const u32x4*)(kp + lane * 16); vv[i] = *(const u32x4*)(kp + 1024 + lane * 16); }
;     ...
;             for (int i = 0; i < 8; ++i) { float vf[16]; unpack16_fp8(vv[i], vf);
; #pragma unroll
;                 for (int d = 0; d < 16; ++d) o[d] += p[i] * vf[d]; }
	v_readfirstlane_b32 s8, v204
	v_readfirstlane_b32 s9, v205
	v_readfirstlane_b32 s10, v206
	v_readfirstlane_b32 s11, v207
	v_readfirstlane_b32 s12, v208
	v_readfirstlane_b32 s13, v209
	v_readfirstlane_b32 s14, v210
	v_readfirstlane_b32 s15, v211
	v_readfirstlane_b32 s16, v212
	v_readfirstlane_b32 s17, v213
	v_readfirstlane_b32 s18, v214
	v_readfirstlane_b32 s19, v215
	v_readfirstlane_b32 s20, v216
	v_readfirstlane_b32 s21, v217
	v_readfirstlane_b32 s22, v218
	v_readfirstlane_b32 s23, v219
	s_cmp_lt_u32 s8, 0x400
	s_cselect_b32 s24, s98, s100
	s_cselect_b32 s25, s99, s101
	s_lshl_b32 s8, s8, 11
	s_add_u32 s24, s24, s8
	s_addc_u32 s25, s25, 0
	global_load_dwordx4 v[132:135], v56, s[24:25]
	s_cmp_lt_u32 s9, 0x400
	s_cselect_b32 s24, s98, s100
	s_cselect_b32 s25, s99, s101
	s_lshl_b32 s9, s9, 11
	s_add_u32 s24, s24, s9
	s_addc_u32 s25, s25, 0
	global_load_dwordx4 v[136:139], v56, s[24:25]
	s_cmp_lt_u32 s10, 0x400
	s_cselect_b32 s24, s98, s100
	s_cselect_b32 s25, s99, s101
	s_lshl_b32 s10, s10, 11
	s_add_u32 s24, s24, s10
	s_addc_u32 s25, s25, 0
	global_load_dwordx4 v[140:143], v56, s[24:25]
	s_cmp_lt_u32 s11, 0x400
	s_cselect_b32 s24, s98, s100
	s_cselect_b32 s25, s99, s101
	s_lshl_b32 s11, s11, 11
	s_add_u32 s24, s24, s11
	s_addc_u32 s25, s25, 0
	global_load_dwordx4 v[144:147], v56, s[24:25]
	s_cmp_lt_u32 s12, 0x400
	s_cselect_b32 s24, s98, s100
	s_cselect_b32 s25, s99, s101
	s_lshl_b32 s12, s12, 11
	s_add_u32 s24, s24, s12
	s_addc_u32 s25, s25, 0
	global_load_dwordx4 v[148:151], v56, s[24:25]
	s_cmp_lt_u32 s13, 0x400
	s_cselect_b32 s24, s98, s100
	s_cselect_b32 s25, s99, s101
	s_lshl_b32 s13, s13, 11
	s_add_u32 s24, s24, s13
	s_addc_u32 s25, s25, 0
	global_load_dwordx4 v[152:155], v56, s[24:25]
	s_cmp_lt_u32 s14, 0x400
	s_cselect_b32 s24, s98, s100
	s_cselect_b32 s25, s99, s101
	s_lshl_b32 s14, s14, 11
	s_add_u32 s24, s24, s14
	s_addc_u32 s25, s25, 0
	global_load_dwordx4 v[156:159], v56, s[24:25]
	s_cmp_lt_u32 s15, 0x400
	s_cselect_b32 s24, s98, s100
	s_cselect_b32 s25, s99, s101
	s_lshl_b32 s15, s15, 11
	s_add_u32 s24, s24, s15
	s_addc_u32 s25, s25, 0
	global_load_dwordx4 v[160:163], v56, s[24:25]
	s_cmp_lt_u32 s16, 0x400
	s_cselect_b32 s24, s98, s100
	s_cselect_b32 s25, s99, s101
	s_lshl_b32 s16, s16, 11
	s_add_u32 s24, s24, s16
	s_addc_u32 s25, s25, 0
	global_load_dwordx4 v[164:167], v56, s[24:25]
	s_cmp_lt_u32 s17, 0x400
	s_cselect_b32 s24, s98, s100
	s_cselect_b32 s25, s99, s101
	s_lshl_b32 s17, s17, 11
	s_add_u32 s24, s24, s17
	s_addc_u32 s25, s25, 0
	global_load_dwordx4 v[168:171], v56, s[24:25]
	s_cmp_lt_u32 s18, 0x400
	s_cselect_b32 s24, s98, s100
	s_cselect_b32 s25, s99, s101
	s_lshl_b32 s18, s18, 11
	s_add_u32 s24, s24, s18
	s_addc_u32 s25, s25, 0
	global_load_dwordx4 v[172:175], v56, s[24:25]
	s_cmp_lt_u32 s19, 0x400
	s_cselect_b32 s24, s98, s100
	s_cselect_b32 s25, s99, s101
	s_lshl_b32 s19, s19, 11
	s_add_u32 s24, s24, s19
	s_addc_u32 s25, s25, 0
	global_load_dwordx4 v[176:179], v56, s[24:25]
	s_cmp_lt_u32 s20, 0x400
	s_cselect_b32 s24, s98, s100
	s_cselect_b32 s25, s99, s101
	s_lshl_b32 s20, s20, 11
	s_add_u32 s24, s24, s20
	s_addc_u32 s25, s25, 0
	global_load_dwordx4 v[180:183], v56, s[24:25]
	s_cmp_lt_u32 s21, 0x400
	s_cselect_b32 s24, s98, s100
	s_cselect_b32 s25, s99, s101
	s_lshl_b32 s21, s21, 11
	s_add_u32 s24, s24, s21
	s_addc_u32 s25, s25, 0
	global_load_dwordx4 v[184:187], v56, s[24:25]
	s_cmp_lt_u32 s22, 0x400
	s_cselect_b32 s24, s98, s100
	s_cselect_b32 s25, s99, s101
	s_lshl_b32 s22, s22, 11
	s_add_u32 s24, s24, s22
	s_addc_u32 s25, s25, 0
	global_load_dwordx4 v[188:191], v56, s[24:25]
	s_cmp_lt_u32 s23, 0x400
	s_cselect_b32 s24, s98, s100
	s_cselect_b32 s25, s99, s101
	s_lshl_b32 s23, s23, 11
	s_add_u32 s24, s24, s23
	s_addc_u32 s25, s25, 0
	global_load_dwordx4 v[192:195], v56, s[24:25]
	s_waitcnt vmcnt(31)
	v_cvt_pk_f32_fp8_e32 v[204:205], v0
	v_cvt_pk_f32_fp8_sdwa v[206:207], v0 src0_sel:WORD_1
	v_pk_fma_f32 v[62:63], v[204:205], v[110:111], v[62:63] op_sel_hi:[1,0,1]
	v_pk_fma_f32 v[64:65], v[206:207], v[110:111], v[64:65] op_sel_hi:[1,0,1]
	v_cvt_pk_f32_fp8_e32 v[208:209], v1
	v_cvt_pk_f32_fp8_sdwa v[210:211], v1 src0_sel:WORD_1
	v_pk_fma_f32 v[66:67], v[208:209], v[110:111], v[66:67] op_sel_hi:[1,0,1]
	v_pk_fma_f32 v[68:69], v[210:211], v[110:111], v[68:69] op_sel_hi:[1,0,1]
	v_cvt_pk_f32_fp8_e32 v[212:213], v2
	v_cvt_pk_f32_fp8_sdwa v[214:215], v2 src0_sel:WORD_1
	v_pk_fma_f32 v[70:71], v[212:213], v[110:111], v[70:71] op_sel_hi:[1,0,1]
	v_pk_fma_f32 v[72:73], v[214:215], v[110:111], v[72:73] op_sel_hi:[1,0,1]
	v_cvt_pk_f32_fp8_e32 v[216:217], v3
	v_cvt_pk_f32_fp8_sdwa v[218:219], v3 src0_sel:WORD_1
	v_pk_fma_f32 v[74:75], v[216:217], v[110:111], v[74:75] op_sel_hi:[1,0,1]
	v_pk_fma_f32 v[76:77], v[218:219], v[110:111], v[76:77] op_sel_hi:[1,0,1]
	s_waitcnt vmcnt(30)
	v_cvt_pk_f32_fp8_e32 v[204:205], v4
	v_cvt_pk_f32_fp8_sdwa v[206:207], v4 src0_sel:WORD_1
	v_pk_fma_f32 v[62:63], v[204:205], v[110:111], v[62:63] op_sel:[0,1,0] op_sel_hi:[1,1,1]
	v_pk_fma_f32 v[64:65], v[206:207], v[110:111], v[64:65] op_sel:[0,1,0] op_sel_hi:[1,1,1]
	v_cvt_pk_f32_fp8_e32 v[208:209], v5
	v_cvt_pk_f32_fp8_sdwa v[210:211], v5 src0_sel:WORD_1
	v_pk_fma_f32 v[66:67], v[208:209], v[110:111], v[66:67] op_sel:[0,1,0] op_sel_hi:[1,1,1]
	v_pk_fma_f32 v[68:69], v[210:211], v[110:111], v[68:69] op_sel:[0,1,0] op_sel_hi:[1,1,1]
	v_cvt_pk_f32_fp8_e32 v[212:213], v6
	v_cvt_pk_f32_fp8_sdwa v[214:215], v6 src0_sel:WORD_1
	v_pk_fma_f32 v[70:71], v[212:213], v[110:111], v[70:71] op_sel:[0,1,0] op_sel_hi:[1,1,1]
	v_pk_fma_f32 v[72:73], v[214:215], v[110:111], v[72:73] op_sel:[0,1,0] op_sel_hi:[1,1,1]
	v_cvt_pk_f32_fp8_e32 v[216:217], v7
	v_cvt_pk_f32_fp8_sdwa v[218:219], v7 src0_sel:WORD_1
	v_pk_fma_f32 v[74:75], v[216:217], v[110:111], v[74:75] op_sel:[0,1,0] op_sel_hi:[1,1,1]
	v_pk_fma_f32 v[76:77], v[218:219], v[110:111], v[76:77] op_sel:[0,1,0] op_sel_hi:[1,1,1]
	s_waitcnt vmcnt(29)
; __device__ __forceinline__ void attn_phase(const Args& a, unsigned char* lds, int lane, int wave) {
;     ...
;             for (int i = 0; i < 8; ++i) { float vf[16]; unpack16_fp8(vv[i], vf);
; #pragma unroll
;                 for (int d = 0; d < 16; ++d) o[d] += p[i] * vf[d]; }
	v_cvt_pk_f32_fp8_e32 v[204:205], v8
	v_cvt_pk_f32_fp8_sdwa v[206:207], v8 src0_sel:WORD_1
	v_pk_fma_f32 v[62:63], v[204:205], v[112:113], v[62:63] op_sel_hi:[1,0,1]
	v_pk_fma_f32 v[64:65], v[206:207], v[112:113], v[64:65] op_sel_hi:[1,0,1]
	v_cvt_pk_f32_fp8_e32 v[208:209], v9
	v_cvt_pk_f32_fp8_sdwa v[210:211], v9 src0_sel:WORD_1
	v_pk_fma_f32 v[66:67], v[208:209], v[112:113], v[66:67] op_sel_hi:[1,0,1]
	v_pk_fma_f32 v[68:69], v[210:211], v[112:113], v[68:69] op_sel_hi:[1,0,1]
	v_cvt_pk_f32_fp8_e32 v[212:213], v10
	v_cvt_pk_f32_fp8_sdwa v[214:215], v10 src0_sel:WORD_1
	v_pk_fma_f32 v[70:71], v[212:213], v[112:113], v[70:71] op_sel_hi:[1,0,1]
	v_pk_fma_f32 v[72:73], v[214:215], v[112:113], v[72:73] op_sel_hi:[1,0,1]
	v_cvt_pk_f32_fp8_e32 v[216:217], v11
	v_cvt_pk_f32_fp8_sdwa v[218:219], v11 src0_sel:WORD_1
	v_pk_fma_f32 v[74:75], v[216:217], v[112:113], v[74:75] op_sel_hi:[1,0,1]
	v_pk_fma_f32 v[76:77], v[218:219], v[112:113], v[76:77] op_sel_hi:[1,0,1]
	s_waitcnt vmcnt(28)
	v_cvt_pk_f32_fp8_e32 v[204:205], v12
	v_cvt_pk_f32_fp8_sdwa v[206:207], v12 src0_sel:WORD_1
	v_pk_fma_f32 v[62:63], v[204:205], v[112:113], v[62:63] op_sel:[0,1,0] op_sel_hi:[1,1,1]
	v_pk_fma_f32 v[64:65], v[206:207], v[112:113], v[64:65] op_sel:[0,1,0] op_sel_hi:[1,1,1]
	v_cvt_pk_f32_fp8_e32 v[208:209], v13
	v_cvt_pk_f32_fp8_sdwa v[210:211], v13 src0_sel:WORD_1
	v_pk_fma_f32 v[66:67], v[208:209], v[112:113], v[66:67] op_sel:[0,1,0] op_sel_hi:[1,1,1]
	v_pk_fma_f32 v[68:69], v[210:211], v[112:113], v[68:69] op_sel:[0,1,0] op_sel_hi:[1,1,1]
	v_cvt_pk_f32_fp8_e32 v[212:213], v14
	v_cvt_pk_f32_fp8_sdwa v[214:215], v14 src0_sel:WORD_1
	v_pk_fma_f32 v[70:71], v[212:213], v[112:113], v[70:71] op_sel:[0,1,0] op_sel_hi:[1,1,1]
	v_pk_fma_f32 v[72:73], v[214:215], v[112:113], v[72:73] op_sel:[0,1,0] op_sel_hi:[1,1,1]
	v_cvt_pk_f32_fp8_e32 v[216:217], v15
	v_cvt_pk_f32_fp8_sdwa v[218:219], v15 src0_sel:WORD_1
	v_pk_fma_f32 v[74:75], v[216:217], v[112:113], v[74:75] op_sel:[0,1,0] op_sel_hi:[1,1,1]
	v_pk_fma_f32 v[76:77], v[218:219], v[112:113], v[76:77] op_sel:[0,1,0] op_sel_hi:[1,1,1]
	s_waitcnt vmcnt(27)
	v_cvt_pk_f32_fp8_e32 v[204:205], v16
	v_cvt_pk_f32_fp8_sdwa v[206:207], v16 src0_sel:WORD_1
	v_pk_fma_f32 v[62:63], v[204:205], v[114:115], v[62:63] op_sel_hi:[1,0,1]
	v_pk_fma_f32 v[64:65], v[206:207], v[114:115], v[64:65] op_sel_hi:[1,0,1]
	v_cvt_pk_f32_fp8_e32 v[208:209], v17
	v_cvt_pk_f32_fp8_sdwa v[210:211], v17 src0_sel:WORD_1
	v_pk_fma_f32 v[66:67], v[208:209], v[114:115], v[66:67] op_sel_hi:[1,0,1]
	v_pk_fma_f32 v[68:69], v[210:211], v[114:115], v[68:69] op_sel_hi:[1,0,1]
	v_cvt_pk_f32_fp8_e32 v[212:213], v18
	v_cvt_pk_f32_fp8_sdwa v[214:215], v18 src0_sel:WORD_1
	v_pk_fma_f32 v[70:71], v[212:213], v[114:115], v[70:71] op_sel_hi:[1,0,1]
	v_pk_fma_f32 v[72:73], v[214:215], v[114:115], v[72:73] op_sel_hi:[1,0,1]
	v_cvt_pk_f32_fp8_e32 v[216:217], v19
	v_cvt_pk_f32_fp8_sdwa v[218:219], v19 src0_sel:WORD_1
	v_pk_fma_f32 v[74:75], v[216:217], v[114:115], v[74:75] op_sel_hi:[1,0,1]
	v_pk_fma_f32 v[76:77], v[218:219], v[114:115], v[76:77] op_sel_hi:[1,0,1]
	s_waitcnt vmcnt(26)
	v_cvt_pk_f32_fp8_e32 v[204:205], v20
	v_cvt_pk_f32_fp8_sdwa v[206:207], v20 src0_sel:WORD_1
	v_pk_fma_f32 v[62:63], v[204:205], v[114:115], v[62:63] op_sel:[0,1,0] op_sel_hi:[1,1,1]
	v_pk_fma_f32 v[64:65], v[206:207], v[114:115], v[64:65] op_sel:[0,1,0] op_sel_hi:[1,1,1]
	v_cvt_pk_f32_fp8_e32 v[208:209], v21
	v_cvt_pk_f32_fp8_sdwa v[210:211], v21 src0_sel:WORD_1
	v_pk_fma_f32 v[66:67], v[208:209], v[114:115], v[66:67] op_sel:[0,1,0] op_sel_hi:[1,1,1]
	v_pk_fma_f32 v[68:69], v[210:211], v[114:115], v[68:69] op_sel:[0,1,0] op_sel_hi:[1,1,1]
	v_cvt_pk_f32_fp8_e32 v[212:213], v22
	v_cvt_pk_f32_fp8_sdwa v[214:215], v22 src0_sel:WORD_1
	v_pk_fma_f32 v[70:71], v[212:213], v[114:115], v[70:71] op_sel:[0,1,0] op_sel_hi:[1,1,1]
	v_pk_fma_f32 v[72:73], v[214:215], v[114:115], v[72:73] op_sel:[0,1,0] op_sel_hi:[1,1,1]
	v_cvt_pk_f32_fp8_e32 v[216:217], v23
	v_cvt_pk_f32_fp8_sdwa v[218:219], v23 src0_sel:WORD_1
	v_pk_fma_f32 v[74:75], v[216:217], v[114:115], v[74:75] op_sel:[0,1,0] op_sel_hi:[1,1,1]
	v_pk_fma_f32 v[76:77], v[218:219], v[114:115], v[76:77] op_sel:[0,1,0] op_sel_hi:[1,1,1]
	s_waitcnt vmcnt(25)
	v_cvt_pk_f32_fp8_e32 v[204:205], v24
	v_cvt_pk_f32_fp8_sdwa v[206:207], v24 src0_sel:WORD_1
	v_pk_fma_f32 v[62:63], v[204:205], v[116:117], v[62:63] op_sel_hi:[1,0,1]
	v_pk_fma_f32 v[64:65], v[206:207], v[116:117], v[64:65] op_sel_hi:[1,0,1]
	v_cvt_pk_f32_fp8_e32 v[208:209], v25
	v_cvt_pk_f32_fp8_sdwa v[210:211], v25 src0_sel:WORD_1
	v_pk_fma_f32 v[66:67], v[208:209], v[116:117], v[66:67] op_sel_hi:[1,0,1]
	v_pk_fma_f32 v[68:69], v[210:211], v[116:117], v[68:69] op_sel_hi:[1,0,1]
	v_cvt_pk_f32_fp8_e32 v[212:213], v26
	v_cvt_pk_f32_fp8_sdwa v[214:215], v26 src0_sel:WORD_1
	v_pk_fma_f32 v[70:71], v[212:213], v[116:117], v[70:71] op_sel_hi:[1,0,1]
	v_pk_fma_f32 v[72:73], v[214:215], v[116:117], v[72:73] op_sel_hi:[1,0,1]
	v_cvt_pk_f32_fp8_e32 v[216:217], v27
	v_cvt_pk_f32_fp8_sdwa v[218:219], v27 src0_sel:WORD_1
	v_pk_fma_f32 v[74:75], v[216:217], v[116:117], v[74:75] op_sel_hi:[1,0,1]
	v_pk_fma_f32 v[76:77], v[218:219], v[116:117], v[76:77] op_sel_hi:[1,0,1]
	s_waitcnt vmcnt(24)
; __device__ __forceinline__ void attn_phase(const Args& a, unsigned char* lds, int lane, int wave) {
;     ...
;             for (int i = 0; i < 8; ++i) { float vf[16]; unpack16_fp8(vv[i], vf);
; #pragma unroll
;                 for (int d = 0; d < 16; ++d) o[d] += p[i] * vf[d]; }
	v_cvt_pk_f32_fp8_e32 v[204:205], v28
	v_cvt_pk_f32_fp8_sdwa v[206:207], v28 src0_sel:WORD_1
	v_pk_fma_f32 v[62:63], v[204:205], v[116:117], v[62:63] op_sel:[0,1,0] op_sel_hi:[1,1,1]
	v_pk_fma_f32 v[64:65], v[206:207], v[116:117], v[64:65] op_sel:[0,1,0] op_sel_hi:[1,1,1]
	v_cvt_pk_f32_fp8_e32 v[208:209], v29
	v_cvt_pk_f32_fp8_sdwa v[210:211], v29 src0_sel:WORD_1
	v_pk_fma_f32 v[66:67], v[208:209], v[116:117], v[66:67] op_sel:[0,1,0] op_sel_hi:[1,1,1]
	v_pk_fma_f32 v[68:69], v[210:211], v[116:117], v[68:69] op_sel:[0,1,0] op_sel_hi:[1,1,1]
	v_cvt_pk_f32_fp8_e32 v[212:213], v30
	v_cvt_pk_f32_fp8_sdwa v[214:215], v30 src0_sel:WORD_1
	v_pk_fma_f32 v[70:71], v[212:213], v[116:117], v[70:71] op_sel:[0,1,0] op_sel_hi:[1,1,1]
	v_pk_fma_f32 v[72:73], v[214:215], v[116:117], v[72:73] op_sel:[0,1,0] op_sel_hi:[1,1,1]
	v_cvt_pk_f32_fp8_e32 v[216:217], v31
	v_cvt_pk_f32_fp8_sdwa v[218:219], v31 src0_sel:WORD_1
	v_pk_fma_f32 v[74:75], v[216:217], v[116:117], v[74:75] op_sel:[0,1,0] op_sel_hi:[1,1,1]
	v_pk_fma_f32 v[76:77], v[218:219], v[116:117], v[76:77] op_sel:[0,1,0] op_sel_hi:[1,1,1]
	s_waitcnt vmcnt(23)
	v_cvt_pk_f32_fp8_e32 v[204:205], v32
	v_cvt_pk_f32_fp8_sdwa v[206:207], v32 src0_sel:WORD_1
	v_pk_fma_f32 v[62:63], v[204:205], v[118:119], v[62:63] op_sel_hi:[1,0,1]
	v_pk_fma_f32 v[64:65], v[206:207], v[118:119], v[64:65] op_sel_hi:[1,0,1]
	v_cvt_pk_f32_fp8_e32 v[208:209], v33
	v_cvt_pk_f32_fp8_sdwa v[210:211], v33 src0_sel:WORD_1
	v_pk_fma_f32 v[66:67], v[208:209], v[118:119], v[66:67] op_sel_hi:[1,0,1]
	v_pk_fma_f32 v[68:69], v[210:211], v[118:119], v[68:69] op_sel_hi:[1,0,1]
	v_cvt_pk_f32_fp8_e32 v[212:213], v34
	v_cvt_pk_f32_fp8_sdwa v[214:215], v34 src0_sel:WORD_1
	v_pk_fma_f32 v[70:71], v[212:213], v[118:119], v[70:71] op_sel_hi:[1,0,1]
	v_pk_fma_f32 v[72:73], v[214:215], v[118:119], v[72:73] op_sel_hi:[1,0,1]
	v_cvt_pk_f32_fp8_e32 v[216:217], v35
	v_cvt_pk_f32_fp8_sdwa v[218:219], v35 src0_sel:WORD_1
	v_pk_fma_f32 v[74:75], v[216:217], v[118:119], v[74:75] op_sel_hi:[1,0,1]
	v_pk_fma_f32 v[76:77], v[218:219], v[118:119], v[76:77] op_sel_hi:[1,0,1]
	s_waitcnt vmcnt(22)
	v_cvt_pk_f32_fp8_e32 v[204:205], v36
	v_cvt_pk_f32_fp8_sdwa v[206:207], v36 src0_sel:WORD_1
	v_pk_fma_f32 v[62:63], v[204:205], v[118:119], v[62:63] op_sel:[0,1,0] op_sel_hi:[1,1,1]
	v_pk_fma_f32 v[64:65], v[206:207], v[118:119], v[64:65] op_sel:[0,1,0] op_sel_hi:[1,1,1]
	v_cvt_pk_f32_fp8_e32 v[208:209], v37
	v_cvt_pk_f32_fp8_sdwa v[210:211], v37 src0_sel:WORD_1
	v_pk_fma_f32 v[66:67], v[208:209], v[118:119], v[66:67] op_sel:[0,1,0] op_sel_hi:[1,1,1]
	v_pk_fma_f32 v[68:69], v[210:211], v[118:119], v[68:69] op_sel:[0,1,0] op_sel_hi:[1,1,1]
	v_cvt_pk_f32_fp8_e32 v[212:213], v38
	v_cvt_pk_f32_fp8_sdwa v[214:215], v38 src0_sel:WORD_1
	v_pk_fma_f32 v[70:71], v[212:213], v[118:119], v[70:71] op_sel:[0,1,0] op_sel_hi:[1,1,1]
	v_pk_fma_f32 v[72:73], v[214:215], v[118:119], v[72:73] op_sel:[0,1,0] op_sel_hi:[1,1,1]
	v_cvt_pk_f32_fp8_e32 v[216:217], v39
	v_cvt_pk_f32_fp8_sdwa v[218:219], v39 src0_sel:WORD_1
	v_pk_fma_f32 v[74:75], v[216:217], v[118:119], v[74:75] op_sel:[0,1,0] op_sel_hi:[1,1,1]
	v_pk_fma_f32 v[76:77], v[218:219], v[118:119], v[76:77] op_sel:[0,1,0] op_sel_hi:[1,1,1]
	s_waitcnt vmcnt(21)
	v_cvt_pk_f32_fp8_e32 v[204:205], v40
	v_cvt_pk_f32_fp8_sdwa v[206:207], v40 src0_sel:WORD_1
	v_pk_fma_f32 v[62:63], v[204:205], v[120:121], v[62:63] op_sel_hi:[1,0,1]
	v_pk_fma_f32 v[64:65], v[206:207], v[120:121], v[64:65] op_sel_hi:[1,0,1]
	v_cvt_pk_f32_fp8_e32 v[208:209], v41
	v_cvt_pk_f32_fp8_sdwa v[210:211], v41 src0_sel:WORD_1
	v_pk_fma_f32 v[66:67], v[208:209], v[120:121], v[66:67] op_sel_hi:[1,0,1]
	v_pk_fma_f32 v[68:69], v[210:211], v[120:121], v[68:69] op_sel_hi:[1,0,1]
	v_cvt_pk_f32_fp8_e32 v[212:213], v42
	v_cvt_pk_f32_fp8_sdwa v[214:215], v42 src0_sel:WORD_1
	v_pk_fma_f32 v[70:71], v[212:213], v[120:121], v[70:71] op_sel_hi:[1,0,1]
	v_pk_fma_f32 v[72:73], v[214:215], v[120:121], v[72:73] op_sel_hi:[1,0,1]
	v_cvt_pk_f32_fp8_e32 v[216:217], v43
	v_cvt_pk_f32_fp8_sdwa v[218:219], v43 src0_sel:WORD_1
	v_pk_fma_f32 v[74:75], v[216:217], v[120:121], v[74:75] op_sel_hi:[1,0,1]
	v_pk_fma_f32 v[76:77], v[218:219], v[120:121], v[76:77] op_sel_hi:[1,0,1]
	s_waitcnt vmcnt(20)
	v_cvt_pk_f32_fp8_e32 v[204:205], v44
	v_cvt_pk_f32_fp8_sdwa v[206:207], v44 src0_sel:WORD_1
	v_pk_fma_f32 v[62:63], v[204:205], v[120:121], v[62:63] op_sel:[0,1,0] op_sel_hi:[1,1,1]
	v_pk_fma_f32 v[64:65], v[206:207], v[120:121], v[64:65] op_sel:[0,1,0] op_sel_hi:[1,1,1]
	v_cvt_pk_f32_fp8_e32 v[208:209], v45
	v_cvt_pk_f32_fp8_sdwa v[210:211], v45 src0_sel:WORD_1
	v_pk_fma_f32 v[66:67], v[208:209], v[120:121], v[66:67] op_sel:[0,1,0] op_sel_hi:[1,1,1]
	v_pk_fma_f32 v[68:69], v[210:211], v[120:121], v[68:69] op_sel:[0,1,0] op_sel_hi:[1,1,1]
	v_cvt_pk_f32_fp8_e32 v[212:213], v46
	v_cvt_pk_f32_fp8_sdwa v[214:215], v46 src0_sel:WORD_1
	v_pk_fma_f32 v[70:71], v[212:213], v[120:121], v[70:71] op_sel:[0,1,0] op_sel_hi:[1,1,1]
	v_pk_fma_f32 v[72:73], v[214:215], v[120:121], v[72:73] op_sel:[0,1,0] op_sel_hi:[1,1,1]
	v_cvt_pk_f32_fp8_e32 v[216:217], v47
	v_cvt_pk_f32_fp8_sdwa v[218:219], v47 src0_sel:WORD_1
	v_pk_fma_f32 v[74:75], v[216:217], v[120:121], v[74:75] op_sel:[0,1,0] op_sel_hi:[1,1,1]
	v_pk_fma_f32 v[76:77], v[218:219], v[120:121], v[76:77] op_sel:[0,1,0] op_sel_hi:[1,1,1]
	s_waitcnt vmcnt(19)
; __device__ __forceinline__ void attn_phase(const Args& a, unsigned char* lds, int lane, int wave) {
;     ...
;             for (int i = 0; i < 8; ++i) { const int idx = (int)(i < 4 ? ida[i & 3] : idb[i & 3]); const unsigned char* kp;
;                 if (!sample) kp = KV8 + (size_t)idx * 2048;
;                 else if (idx < 1024) kp = CKV8 + (size_t)(bb * 1024 + idx) * 2048;
;                 else kp = KV8 + (size_t)(TP + bb * 64 + idx - 1024) * 2048;
;                 kk[i] = *(const u32x4*)(kp + lane * 16); vv[i] = *(const u32x4*)(kp + 1024 + lane * 16); }
;     ...
;             for (int i = 0; i < 8; ++i) { float vf[16]; unpack16_fp8(vv[i], vf);
; #pragma unroll
;                 for (int d = 0; d < 16; ++d) o[d] += p[i] * vf[d]; }
	v_cvt_pk_f32_fp8_e32 v[204:205], v48
	v_cvt_pk_f32_fp8_sdwa v[206:207], v48 src0_sel:WORD_1
	v_pk_fma_f32 v[62:63], v[204:205], v[122:123], v[62:63] op_sel_hi:[1,0,1]
	v_pk_fma_f32 v[64:65], v[206:207], v[122:123], v[64:65] op_sel_hi:[1,0,1]
	v_cvt_pk_f32_fp8_e32 v[208:209], v49
	v_cvt_pk_f32_fp8_sdwa v[210:211], v49 src0_sel:WORD_1
	v_pk_fma_f32 v[66:67], v[208:209], v[122:123], v[66:67] op_sel_hi:[1,0,1]
	v_pk_fma_f32 v[68:69], v[210:211], v[122:123], v[68:69] op_sel_hi:[1,0,1]
	v_cvt_pk_f32_fp8_e32 v[212:213], v50
	v_cvt_pk_f32_fp8_sdwa v[214:215], v50 src0_sel:WORD_1
	v_pk_fma_f32 v[70:71], v[212:213], v[122:123], v[70:71] op_sel_hi:[1,0,1]
	v_pk_fma_f32 v[72:73], v[214:215], v[122:123], v[72:73] op_sel_hi:[1,0,1]
	v_cvt_pk_f32_fp8_e32 v[216:217], v51
	v_cvt_pk_f32_fp8_sdwa v[218:219], v51 src0_sel:WORD_1
	v_pk_fma_f32 v[74:75], v[216:217], v[122:123], v[74:75] op_sel_hi:[1,0,1]
	v_pk_fma_f32 v[76:77], v[218:219], v[122:123], v[76:77] op_sel_hi:[1,0,1]
	s_waitcnt vmcnt(18)
	v_cvt_pk_f32_fp8_e32 v[204:205], v52
	v_cvt_pk_f32_fp8_sdwa v[206:207], v52 src0_sel:WORD_1
	v_pk_fma_f32 v[62:63], v[204:205], v[122:123], v[62:63] op_sel:[0,1,0] op_sel_hi:[1,1,1]
	v_pk_fma_f32 v[64:65], v[206:207], v[122:123], v[64:65] op_sel:[0,1,0] op_sel_hi:[1,1,1]
	v_cvt_pk_f32_fp8_e32 v[208:209], v53
	v_cvt_pk_f32_fp8_sdwa v[210:211], v53 src0_sel:WORD_1
	v_pk_fma_f32 v[66:67], v[208:209], v[122:123], v[66:67] op_sel:[0,1,0] op_sel_hi:[1,1,1]
	v_pk_fma_f32 v[68:69], v[210:211], v[122:123], v[68:69] op_sel:[0,1,0] op_sel_hi:[1,1,1]
	v_cvt_pk_f32_fp8_e32 v[212:213], v54
	v_cvt_pk_f32_fp8_sdwa v[214:215], v54 src0_sel:WORD_1
	v_pk_fma_f32 v[70:71], v[212:213], v[122:123], v[70:71] op_sel:[0,1,0] op_sel_hi:[1,1,1]
	v_pk_fma_f32 v[72:73], v[214:215], v[122:123], v[72:73] op_sel:[0,1,0] op_sel_hi:[1,1,1]
	v_cvt_pk_f32_fp8_e32 v[216:217], v55
	v_cvt_pk_f32_fp8_sdwa v[218:219], v55 src0_sel:WORD_1
	v_pk_fma_f32 v[74:75], v[216:217], v[122:123], v[74:75] op_sel:[0,1,0] op_sel_hi:[1,1,1]
	v_pk_fma_f32 v[76:77], v[218:219], v[122:123], v[76:77] op_sel:[0,1,0] op_sel_hi:[1,1,1]
	s_waitcnt vmcnt(17)
	v_cvt_pk_f32_fp8_e32 v[204:205], v196
	v_cvt_pk_f32_fp8_sdwa v[206:207], v196 src0_sel:WORD_1
	v_pk_fma_f32 v[62:63], v[204:205], v[124:125], v[62:63] op_sel_hi:[1,0,1]
	v_pk_fma_f32 v[64:65], v[206:207], v[124:125], v[64:65] op_sel_hi:[1,0,1]
	v_cvt_pk_f32_fp8_e32 v[208:209], v197
	v_cvt_pk_f32_fp8_sdwa v[210:211], v197 src0_sel:WORD_1
	v_pk_fma_f32 v[66:67], v[208:209], v[124:125], v[66:67] op_sel_hi:[1,0,1]
	v_pk_fma_f32 v[68:69], v[210:211], v[124:125], v[68:69] op_sel_hi:[1,0,1]
	v_cvt_pk_f32_fp8_e32 v[212:213], v198
	v_cvt_pk_f32_fp8_sdwa v[214:215], v198 src0_sel:WORD_1
	v_pk_fma_f32 v[70:71], v[212:213], v[124:125], v[70:71] op_sel_hi:[1,0,1]
	v_pk_fma_f32 v[72:73], v[214:215], v[124:125], v[72:73] op_sel_hi:[1,0,1]
	v_cvt_pk_f32_fp8_e32 v[216:217], v199
	v_cvt_pk_f32_fp8_sdwa v[218:219], v199 src0_sel:WORD_1
	v_pk_fma_f32 v[74:75], v[216:217], v[124:125], v[74:75] op_sel_hi:[1,0,1]
	v_pk_fma_f32 v[76:77], v[218:219], v[124:125], v[76:77] op_sel_hi:[1,0,1]
	s_waitcnt vmcnt(16)
	v_cvt_pk_f32_fp8_e32 v[204:205], v200
	v_cvt_pk_f32_fp8_sdwa v[206:207], v200 src0_sel:WORD_1
	v_pk_fma_f32 v[62:63], v[204:205], v[124:125], v[62:63] op_sel:[0,1,0] op_sel_hi:[1,1,1]
	v_pk_fma_f32 v[64:65], v[206:207], v[124:125], v[64:65] op_sel:[0,1,0] op_sel_hi:[1,1,1]
	v_cvt_pk_f32_fp8_e32 v[208:209], v201
	v_cvt_pk_f32_fp8_sdwa v[210:211], v201 src0_sel:WORD_1
	v_pk_fma_f32 v[66:67], v[208:209], v[124:125], v[66:67] op_sel:[0,1,0] op_sel_hi:[1,1,1]
	v_pk_fma_f32 v[68:69], v[210:211], v[124:125], v[68:69] op_sel:[0,1,0] op_sel_hi:[1,1,1]
	v_cvt_pk_f32_fp8_e32 v[212:213], v202
	v_cvt_pk_f32_fp8_sdwa v[214:215], v202 src0_sel:WORD_1
	v_pk_fma_f32 v[70:71], v[212:213], v[124:125], v[70:71] op_sel:[0,1,0] op_sel_hi:[1,1,1]
	v_pk_fma_f32 v[72:73], v[214:215], v[124:125], v[72:73] op_sel:[0,1,0] op_sel_hi:[1,1,1]
	v_cvt_pk_f32_fp8_e32 v[216:217], v203
	v_cvt_pk_f32_fp8_sdwa v[218:219], v203 src0_sel:WORD_1
	v_pk_fma_f32 v[74:75], v[216:217], v[124:125], v[74:75] op_sel:[0,1,0] op_sel_hi:[1,1,1]
	v_pk_fma_f32 v[76:77], v[218:219], v[124:125], v[76:77] op_sel:[0,1,0] op_sel_hi:[1,1,1]
	s_cmp_lt_u32 s8, 0x200000
	s_cselect_b32 s24, s98, s100
	s_cselect_b32 s25, s99, s101
	s_add_u32 s24, s24, s8
	s_addc_u32 s25, s25, 0
	global_load_dwordx4 v[0:3], v56, s[24:25] offset:1024
	s_cmp_lt_u32 s9, 0x200000
	s_cselect_b32 s24, s98, s100
	s_cselect_b32 s25, s99, s101
	s_add_u32 s24, s24, s9
	s_addc_u32 s25, s25, 0
	global_load_dwordx4 v[4:7], v56, s[24:25] offset:1024
	s_cmp_lt_u32 s10, 0x200000
	s_cselect_b32 s24, s98, s100
	s_cselect_b32 s25, s99, s101
	s_add_u32 s24, s24, s10
	s_addc_u32 s25, s25, 0
	global_load_dwordx4 v[8:11], v56, s[24:25] offset:1024
	s_cmp_lt_u32 s11, 0x200000
	s_cselect_b32 s24, s98, s100
	s_cselect_b32 s25, s99, s101
	s_add_u32 s24, s24, s11
	s_addc_u32 s25, s25, 0
	global_load_dwordx4 v[12:15], v56, s[24:25] offset:1024
	s_cmp_lt_u32 s12, 0x200000
	s_cselect_b32 s24, s98, s100
	s_cselect_b32 s25, s99, s101
	s_add_u32 s24, s24, s12
	s_addc_u32 s25, s25, 0
	global_load_dwordx4 v[16:19], v56, s[24:25] offset:1024
	s_cmp_lt_u32 s13, 0x200000
	s_cselect_b32 s24, s98, s100
	s_cselect_b32 s25, s99, s101
	s_add_u32 s24, s24, s13
	s_addc_u32 s25, s25, 0
	global_load_dwordx4 v[20:23], v56, s[24:25] offset:1024
	s_cmp_lt_u32 s14, 0x200000
	s_cselect_b32 s24, s98, s100
	s_cselect_b32 s25, s99, s101
	s_add_u32 s24, s24, s14
	s_addc_u32 s25, s25, 0
	global_load_dwordx4 v[24:27], v56, s[24:25] offset:1024
	s_cmp_lt_u32 s15, 0x200000
	s_cselect_b32 s24, s98, s100
	s_cselect_b32 s25, s99, s101
; __device__ __forceinline__ void attn_phase(const Args& a, unsigned char* lds, int lane, int wave) {
;     ...
;         for (int j = 0; j < nsel; j += 8) {
;             const u32x4 ida = *(const u32x4*)(sel + j), idb = *(const u32x4*)(sel + j + 4);
;             u32x4 kk[8], vv[8];
; #pragma unroll
;             for (int i = 0; i < 8; ++i) { const int idx = (int)(i < 4 ? ida[i & 3] : idb[i & 3]); const unsigned char* kp;
;                 if (!sample) kp = KV8 + (size_t)idx * 2048;
;                 else if (idx < 1024) kp = CKV8 + (size_t)(bb * 1024 + idx) * 2048;
;                 else kp = KV8 + (size_t)(TP + bb * 64 + idx - 1024) * 2048;
;                 kk[i] = *(const u32x4*)(kp + lane * 16); vv[i] = *(const u32x4*)(kp + 1024 + lane * 16); }
;             float s[8];
; #pragma unroll
;             for (int i = 0; i < 8; ++i) { float kf[16]; unpack16_fp8(kk[i], kf); float d0 = 0.f, d1 = 0.f;
; #pragma unroll
;                 for (int x = 0; x < 16; x += 2) { d0 += q[x] * kf[x]; d1 += q[x + 1] * kf[x + 1]; }
;                 float d = d0 + d1;
;                 d += __shfl_xor(d, 1); d += __shfl_xor(d, 2); d += __shfl_xor(d, 4); s[i] = d; }
	s_add_u32 s24, s24, s15
	s_addc_u32 s25, s25, 0
	global_load_dwordx4 v[28:31], v56, s[24:25] offset:1024
	s_cmp_lt_u32 s16, 0x200000
	s_cselect_b32 s24, s98, s100
	s_cselect_b32 s25, s99, s101
	s_add_u32 s24, s24, s16
	s_addc_u32 s25, s25, 0
	global_load_dwordx4 v[32:35], v56, s[24:25] offset:1024
	s_cmp_lt_u32 s17, 0x200000
	s_cselect_b32 s24, s98, s100
	s_cselect_b32 s25, s99, s101
	s_add_u32 s24, s24, s17
	s_addc_u32 s25, s25, 0
	global_load_dwordx4 v[36:39], v56, s[24:25] offset:1024
	s_cmp_lt_u32 s18, 0x200000
	s_cselect_b32 s24, s98, s100
	s_cselect_b32 s25, s99, s101
	s_add_u32 s24, s24, s18
	s_addc_u32 s25, s25, 0
	global_load_dwordx4 v[40:43], v56, s[24:25] offset:1024
	s_cmp_lt_u32 s19, 0x200000
	s_cselect_b32 s24, s98, s100
	s_cselect_b32 s25, s99, s101
	s_add_u32 s24, s24, s19
	s_addc_u32 s25, s25, 0
	global_load_dwordx4 v[44:47], v56, s[24:25] offset:1024
	s_cmp_lt_u32 s20, 0x200000
	s_cselect_b32 s24, s98, s100
	s_cselect_b32 s25, s99, s101
	s_add_u32 s24, s24, s20
	s_addc_u32 s25, s25, 0
	global_load_dwordx4 v[48:51], v56, s[24:25] offset:1024
	s_cmp_lt_u32 s21, 0x200000
	s_cselect_b32 s24, s98, s100
	s_cselect_b32 s25, s99, s101
	s_add_u32 s24, s24, s21
	s_addc_u32 s25, s25, 0
	global_load_dwordx4 v[52:55], v56, s[24:25] offset:1024
	s_cmp_lt_u32 s22, 0x200000
	s_cselect_b32 s24, s98, s100
	s_cselect_b32 s25, s99, s101
	s_add_u32 s24, s24, s22
	s_addc_u32 s25, s25, 0
	global_load_dwordx4 v[196:199], v56, s[24:25] offset:1024
	s_cmp_lt_u32 s23, 0x200000
	s_cselect_b32 s24, s98, s100
	s_cselect_b32 s25, s99, s101
	s_add_u32 s24, s24, s23
	s_addc_u32 s25, s25, 0
	global_load_dwordx4 v[200:203], v56, s[24:25] offset:1024
	s_add_i32 s3, s3, -1
	s_cmp_lg_u32 s3, 0
	s_cbranch_scc1 .Lat_blk
	s_waitcnt vmcnt(30)
	v_cvt_pk_f32_fp8_e32 v[204:205], v132
	v_cvt_pk_f32_fp8_e32 v[206:207], v136
	v_pk_mul_f32 v[220:221], v[204:205], v[78:79]
	v_pk_mul_f32 v[222:223], v[206:207], v[78:79]
	v_cvt_pk_f32_fp8_sdwa v[208:209], v132 src0_sel:WORD_1
	v_cvt_pk_f32_fp8_sdwa v[210:211], v136 src0_sel:WORD_1
	v_pk_fma_f32 v[220:221], v[208:209], v[80:81], v[220:221]
	v_pk_fma_f32 v[222:223], v[210:211], v[80:81], v[222:223]
	v_cvt_pk_f32_fp8_e32 v[212:213], v133
	v_cvt_pk_f32_fp8_e32 v[214:215], v137
	v_pk_fma_f32 v[220:221], v[212:213], v[82:83], v[220:221]
	v_pk_fma_f32 v[222:223], v[214:215], v[82:83], v[222:223]
	v_cvt_pk_f32_fp8_sdwa v[216:217], v133 src0_sel:WORD_1
	v_cvt_pk_f32_fp8_sdwa v[218:219], v137 src0_sel:WORD_1
	v_pk_fma_f32 v[220:221], v[216:217], v[84:85], v[220:221]
	v_pk_fma_f32 v[222:223], v[218:219], v[84:85], v[222:223]
	v_cvt_pk_f32_fp8_e32 v[204:205], v134
	v_cvt_pk_f32_fp8_e32 v[206:207], v138
	v_pk_fma_f32 v[220:221], v[204:205], v[86:87], v[220:221]
	v_pk_fma_f32 v[222:223], v[206:207], v[86:87], v[222:223]
	v_cvt_pk_f32_fp8_sdwa v[208:209], v134 src0_sel:WORD_1
	v_cvt_pk_f32_fp8_sdwa v[210:211], v138 src0_sel:WORD_1
	v_pk_fma_f32 v[220:221], v[208:209], v[88:89], v[220:221]
	v_pk_fma_f32 v[222:223], v[210:211], v[88:89], v[222:223]
	v_cvt_pk_f32_fp8_e32 v[212:213], v135
	v_cvt_pk_f32_fp8_e32 v[214:215], v139
	v_pk_fma_f32 v[220:221], v[212:213], v[90:91], v[220:221]
	v_pk_fma_f32 v[222:223], v[214:215], v[90:91], v[222:223]
	v_cvt_pk_f32_fp8_sdwa v[216:217], v135 src0_sel:WORD_1
	v_cvt_pk_f32_fp8_sdwa v[218:219], v139 src0_sel:WORD_1
	v_pk_fma_f32 v[220:221], v[216:217], v[92:93], v[220:221]
	v_pk_fma_f32 v[222:223], v[218:219], v[92:93], v[222:223]
	s_waitcnt vmcnt(28)
	v_cvt_pk_f32_fp8_e32 v[204:205], v140
	v_cvt_pk_f32_fp8_e32 v[206:207], v144
	v_pk_mul_f32 v[224:225], v[204:205], v[78:79]
	v_pk_mul_f32 v[226:227], v[206:207], v[78:79]
	v_cvt_pk_f32_fp8_sdwa v[208:209], v140 src0_sel:WORD_1
	v_cvt_pk_f32_fp8_sdwa v[210:211], v144 src0_sel:WORD_1
	v_pk_fma_f32 v[224:225], v[208:209], v[80:81], v[224:225]
	v_pk_fma_f32 v[226:227], v[210:211], v[80:81], v[226:227]
	v_cvt_pk_f32_fp8_e32 v[212:213], v141
	v_cvt_pk_f32_fp8_e32 v[214:215], v145
	v_pk_fma_f32 v[224:225], v[212:213], v[82:83], v[224:225]
	v_pk_fma_f32 v[226:227], v[214:215], v[82:83], v[226:227]
	v_cvt_pk_f32_fp8_sdwa v[216:217], v141 src0_sel:WORD_1
	v_cvt_pk_f32_fp8_sdwa v[218:219], v145 src0_sel:WORD_1
	v_pk_fma_f32 v[224:225], v[216:217], v[84:85], v[224:225]
	v_pk_fma_f32 v[226:227], v[218:219], v[84:85], v[226:227]
	v_cvt_pk_f32_fp8_e32 v[204:205], v142
	v_cvt_pk_f32_fp8_e32 v[206:207], v146
	v_pk_fma_f32 v[224:225], v[204:205], v[86:87], v[224:225]
	v_pk_fma_f32 v[226:227], v[206:207], v[86:87], v[226:227]
	v_cvt_pk_f32_fp8_sdwa v[208:209], v142 src0_sel:WORD_1
	v_cvt_pk_f32_fp8_sdwa v[210:211], v146 src0_sel:WORD_1
	v_pk_fma_f32 v[224:225], v[208:209], v[88:89], v[224:225]
	v_pk_fma_f32 v[226:227], v[210:211], v[88:89], v[226:227]
	v_cvt_pk_f32_fp8_e32 v[212:213], v143
	v_cvt_pk_f32_fp8_e32 v[214:215], v147
	v_pk_fma_f32 v[224:225], v[212:213], v[90:91], v[224:225]
	v_pk_fma_f32 v[226:227], v[214:215], v[90:91], v[226:227]
	v_cvt_pk_f32_fp8_sdwa v[216:217], v143 src0_sel:WORD_1
	v_cvt_pk_f32_fp8_sdwa v[218:219], v147 src0_sel:WORD_1
	v_pk_fma_f32 v[224:225], v[216:217], v[92:93], v[224:225]
	v_pk_fma_f32 v[226:227], v[218:219], v[92:93], v[226:227]
	v_add_f32_e32 v110, v220, v221
	v_add_f32_e32 v111, v222, v223
	v_add_f32_e32 v112, v224, v225
	v_add_f32_e32 v113, v226, v227
	v_add_f32_dpp v110, v110, v110 quad_perm:[1,0,3,2] row_mask:0xf bank_mask:0xf
	v_add_f32_dpp v111, v111, v111 quad_perm:[1,0,3,2] row_mask:0xf bank_mask:0xf
	v_add_f32_dpp v112, v112, v112 quad_perm:[1,0,3,2] row_mask:0xf bank_mask:0xf
	v_add_f32_dpp v113, v113, v113 quad_perm:[1,0,3,2] row_mask:0xf bank_mask:0xf
	v_add_f32_dpp v110, v110, v110 quad_perm:[2,3,0,1] row_mask:0xf bank_mask:0xf
	v_add_f32_dpp v111, v111, v111 quad_perm:[2,3,0,1] row_mask:0xf bank_mask:0xf
	v_add_f32_dpp v112, v112, v112 quad_perm:[2,3,0,1] row_mask:0xf bank_mask:0xf
	v_add_f32_dpp v113, v113, v113 quad_perm:[2,3,0,1] row_mask:0xf bank_mask:0xf
	v_add_f32_dpp v110, v110, v110 row_half_mirror row_mask:0xf bank_mask:0xf
	v_add_f32_dpp v111, v111, v111 row_half_mirror row_mask:0xf bank_mask:0xf
	v_add_f32_dpp v112, v112, v112 row_half_mirror row_mask:0xf bank_mask:0xf
	v_add_f32_dpp v113, v113, v113 row_half_mirror row_mask:0xf bank_mask:0xf
	s_waitcnt vmcnt(26)
; __device__ __forceinline__ void attn_phase(const Args& a, unsigned char* lds, int lane, int wave) {
;     ...
;             for (int i = 0; i < 8; ++i) { float kf[16]; unpack16_fp8(kk[i], kf); float d0 = 0.f, d1 = 0.f;
; #pragma unroll
;                 for (int x = 0; x < 16; x += 2) { d0 += q[x] * kf[x]; d1 += q[x + 1] * kf[x + 1]; }
;                 float d = d0 + d1;
;                 d += __shfl_xor(d, 1); d += __shfl_xor(d, 2); d += __shfl_xor(d, 4); s[i] = d; }
	v_cvt_pk_f32_fp8_e32 v[204:205], v148
	v_cvt_pk_f32_fp8_e32 v[206:207], v152
	v_pk_mul_f32 v[220:221], v[204:205], v[78:79]
	v_pk_mul_f32 v[222:223], v[206:207], v[78:79]
	v_cvt_pk_f32_fp8_sdwa v[208:209], v148 src0_sel:WORD_1
	v_cvt_pk_f32_fp8_sdwa v[210:211], v152 src0_sel:WORD_1
	v_pk_fma_f32 v[220:221], v[208:209], v[80:81], v[220:221]
	v_pk_fma_f32 v[222:223], v[210:211], v[80:81], v[222:223]
	v_cvt_pk_f32_fp8_e32 v[212:213], v149
	v_cvt_pk_f32_fp8_e32 v[214:215], v153
	v_pk_fma_f32 v[220:221], v[212:213], v[82:83], v[220:221]
	v_pk_fma_f32 v[222:223], v[214:215], v[82:83], v[222:223]
	v_cvt_pk_f32_fp8_sdwa v[216:217], v149 src0_sel:WORD_1
	v_cvt_pk_f32_fp8_sdwa v[218:219], v153 src0_sel:WORD_1
	v_pk_fma_f32 v[220:221], v[216:217], v[84:85], v[220:221]
	v_pk_fma_f32 v[222:223], v[218:219], v[84:85], v[222:223]
	v_cvt_pk_f32_fp8_e32 v[204:205], v150
	v_cvt_pk_f32_fp8_e32 v[206:207], v154
	v_pk_fma_f32 v[220:221], v[204:205], v[86:87], v[220:221]
	v_pk_fma_f32 v[222:223], v[206:207], v[86:87], v[222:223]
	v_cvt_pk_f32_fp8_sdwa v[208:209], v150 src0_sel:WORD_1
	v_cvt_pk_f32_fp8_sdwa v[210:211], v154 src0_sel:WORD_1
	v_pk_fma_f32 v[220:221], v[208:209], v[88:89], v[220:221]
	v_pk_fma_f32 v[222:223], v[210:211], v[88:89], v[222:223]
	v_cvt_pk_f32_fp8_e32 v[212:213], v151
	v_cvt_pk_f32_fp8_e32 v[214:215], v155
	v_pk_fma_f32 v[220:221], v[212:213], v[90:91], v[220:221]
	v_pk_fma_f32 v[222:223], v[214:215], v[90:91], v[222:223]
	v_cvt_pk_f32_fp8_sdwa v[216:217], v151 src0_sel:WORD_1
	v_cvt_pk_f32_fp8_sdwa v[218:219], v155 src0_sel:WORD_1
	v_pk_fma_f32 v[220:221], v[216:217], v[92:93], v[220:221]
	v_pk_fma_f32 v[222:223], v[218:219], v[92:93], v[222:223]
	s_waitcnt vmcnt(24)
	v_cvt_pk_f32_fp8_e32 v[204:205], v156
	v_cvt_pk_f32_fp8_e32 v[206:207], v160
	v_pk_mul_f32 v[224:225], v[204:205], v[78:79]
	v_pk_mul_f32 v[226:227], v[206:207], v[78:79]
	v_cvt_pk_f32_fp8_sdwa v[208:209], v156 src0_sel:WORD_1
	v_cvt_pk_f32_fp8_sdwa v[210:211], v160 src0_sel:WORD_1
	v_pk_fma_f32 v[224:225], v[208:209], v[80:81], v[224:225]
	v_pk_fma_f32 v[226:227], v[210:211], v[80:81], v[226:227]
	v_cvt_pk_f32_fp8_e32 v[212:213], v157
	v_cvt_pk_f32_fp8_e32 v[214:215], v161
	v_pk_fma_f32 v[224:225], v[212:213], v[82:83], v[224:225]
	v_pk_fma_f32 v[226:227], v[214:215], v[82:83], v[226:227]
	v_cvt_pk_f32_fp8_sdwa v[216:217], v157 src0_sel:WORD_1
	v_cvt_pk_f32_fp8_sdwa v[218:219], v161 src0_sel:WORD_1
	v_pk_fma_f32 v[224:225], v[216:217], v[84:85], v[224:225]
	v_pk_fma_f32 v[226:227], v[218:219], v[84:85], v[226:227]
	v_cvt_pk_f32_fp8_e32 v[204:205], v158
	v_cvt_pk_f32_fp8_e32 v[206:207], v162
	v_pk_fma_f32 v[224:225], v[204:205], v[86:87], v[224:225]
	v_pk_fma_f32 v[226:227], v[206:207], v[86:87], v[226:227]
	v_cvt_pk_f32_fp8_sdwa v[208:209], v158 src0_sel:WORD_1
	v_cvt_pk_f32_fp8_sdwa v[210:211], v162 src0_sel:WORD_1
	v_pk_fma_f32 v[224:225], v[208:209], v[88:89], v[224:225]
	v_pk_fma_f32 v[226:227], v[210:211], v[88:89], v[226:227]
	v_cvt_pk_f32_fp8_e32 v[212:213], v159
	v_cvt_pk_f32_fp8_e32 v[214:215], v163
	v_pk_fma_f32 v[224:225], v[212:213], v[90:91], v[224:225]
	v_pk_fma_f32 v[226:227], v[214:215], v[90:91], v[226:227]
	v_cvt_pk_f32_fp8_sdwa v[216:217], v159 src0_sel:WORD_1
	v_cvt_pk_f32_fp8_sdwa v[218:219], v163 src0_sel:WORD_1
	v_pk_fma_f32 v[224:225], v[216:217], v[92:93], v[224:225]
	v_pk_fma_f32 v[226:227], v[218:219], v[92:93], v[226:227]
	v_add_f32_e32 v114, v220, v221
	v_add_f32_e32 v115, v222, v223
	v_add_f32_e32 v116, v224, v225
	v_add_f32_e32 v117, v226, v227
	v_add_f32_dpp v114, v114, v114 quad_perm:[1,0,3,2] row_mask:0xf bank_mask:0xf
	v_add_f32_dpp v115, v115, v115 quad_perm:[1,0,3,2] row_mask:0xf bank_mask:0xf
	v_add_f32_dpp v116, v116, v116 quad_perm:[1,0,3,2] row_mask:0xf bank_mask:0xf
	v_add_f32_dpp v117, v117, v117 quad_perm:[1,0,3,2] row_mask:0xf bank_mask:0xf
	v_add_f32_dpp v114, v114, v114 quad_perm:[2,3,0,1] row_mask:0xf bank_mask:0xf
	v_add_f32_dpp v115, v115, v115 quad_perm:[2,3,0,1] row_mask:0xf bank_mask:0xf
	v_add_f32_dpp v116, v116, v116 quad_perm:[2,3,0,1] row_mask:0xf bank_mask:0xf
	v_add_f32_dpp v117, v117, v117 quad_perm:[2,3,0,1] row_mask:0xf bank_mask:0xf
	v_add_f32_dpp v114, v114, v114 row_half_mirror row_mask:0xf bank_mask:0xf
	v_add_f32_dpp v115, v115, v115 row_half_mirror row_mask:0xf bank_mask:0xf
	v_add_f32_dpp v116, v116, v116 row_half_mirror row_mask:0xf bank_mask:0xf
	v_add_f32_dpp v117, v117, v117 row_half_mirror row_mask:0xf bank_mask:0xf
	s_waitcnt vmcnt(22)
	v_cvt_pk_f32_fp8_e32 v[204:205], v164
	v_cvt_pk_f32_fp8_e32 v[206:207], v168
	v_pk_mul_f32 v[220:221], v[204:205], v[78:79]
	v_pk_mul_f32 v[222:223], v[206:207], v[78:79]
	v_cvt_pk_f32_fp8_sdwa v[208:209], v164 src0_sel:WORD_1
	v_cvt_pk_f32_fp8_sdwa v[210:211], v168 src0_sel:WORD_1
	v_pk_fma_f32 v[220:221], v[208:209], v[80:81], v[220:221]
	v_pk_fma_f32 v[222:223], v[210:211], v[80:81], v[222:223]
	v_cvt_pk_f32_fp8_e32 v[212:213], v165
	v_cvt_pk_f32_fp8_e32 v[214:215], v169
	v_pk_fma_f32 v[220:221], v[212:213], v[82:83], v[220:221]
	v_pk_fma_f32 v[222:223], v[214:215], v[82:83], v[222:223]
	v_cvt_pk_f32_fp8_sdwa v[216:217], v165 src0_sel:WORD_1
	v_cvt_pk_f32_fp8_sdwa v[218:219], v169 src0_sel:WORD_1
	v_pk_fma_f32 v[220:221], v[216:217], v[84:85], v[220:221]
	v_pk_fma_f32 v[222:223], v[218:219], v[84:85], v[222:223]
	v_cvt_pk_f32_fp8_e32 v[204:205], v166
	v_cvt_pk_f32_fp8_e32 v[206:207], v170
	v_pk_fma_f32 v[220:221], v[204:205], v[86:87], v[220:221]
	v_pk_fma_f32 v[222:223], v[206:207], v[86:87], v[222:223]
	v_cvt_pk_f32_fp8_sdwa v[208:209], v166 src0_sel:WORD_1
	v_cvt_pk_f32_fp8_sdwa v[210:211], v170 src0_sel:WORD_1
	v_pk_fma_f32 v[220:221], v[208:209], v[88:89], v[220:221]
	v_pk_fma_f32 v[222:223], v[210:211], v[88:89], v[222:223]
	v_cvt_pk_f32_fp8_e32 v[212:213], v167
	v_cvt_pk_f32_fp8_e32 v[214:215], v171
	v_pk_fma_f32 v[220:221], v[212:213], v[90:91], v[220:221]
	v_pk_fma_f32 v[222:223], v[214:215], v[90:91], v[222:223]
	v_cvt_pk_f32_fp8_sdwa v[216:217], v167 src0_sel:WORD_1
	v_cvt_pk_f32_fp8_sdwa v[218:219], v171 src0_sel:WORD_1
	v_pk_fma_f32 v[220:221], v[216:217], v[92:93], v[220:221]
	v_pk_fma_f32 v[222:223], v[218:219], v[92:93], v[222:223]
	s_waitcnt vmcnt(20)
; __device__ __forceinline__ void attn_phase(const Args& a, unsigned char* lds, int lane, int wave) {
;     ...
;             for (int i = 0; i < 8; ++i) { float kf[16]; unpack16_fp8(kk[i], kf); float d0 = 0.f, d1 = 0.f;
; #pragma unroll
;                 for (int x = 0; x < 16; x += 2) { d0 += q[x] * kf[x]; d1 += q[x + 1] * kf[x + 1]; }
;                 float d = d0 + d1;
;                 d += __shfl_xor(d, 1); d += __shfl_xor(d, 2); d += __shfl_xor(d, 4); s[i] = d; }
	v_cvt_pk_f32_fp8_e32 v[204:205], v172
	v_cvt_pk_f32_fp8_e32 v[206:207], v176
	v_pk_mul_f32 v[224:225], v[204:205], v[78:79]
	v_pk_mul_f32 v[226:227], v[206:207], v[78:79]
	v_cvt_pk_f32_fp8_sdwa v[208:209], v172 src0_sel:WORD_1
	v_cvt_pk_f32_fp8_sdwa v[210:211], v176 src0_sel:WORD_1
	v_pk_fma_f32 v[224:225], v[208:209], v[80:81], v[224:225]
	v_pk_fma_f32 v[226:227], v[210:211], v[80:81], v[226:227]
	v_cvt_pk_f32_fp8_e32 v[212:213], v173
	v_cvt_pk_f32_fp8_e32 v[214:215], v177
	v_pk_fma_f32 v[224:225], v[212:213], v[82:83], v[224:225]
	v_pk_fma_f32 v[226:227], v[214:215], v[82:83], v[226:227]
	v_cvt_pk_f32_fp8_sdwa v[216:217], v173 src0_sel:WORD_1
	v_cvt_pk_f32_fp8_sdwa v[218:219], v177 src0_sel:WORD_1
	v_pk_fma_f32 v[224:225], v[216:217], v[84:85], v[224:225]
	v_pk_fma_f32 v[226:227], v[218:219], v[84:85], v[226:227]
	v_cvt_pk_f32_fp8_e32 v[204:205], v174
	v_cvt_pk_f32_fp8_e32 v[206:207], v178
	v_pk_fma_f32 v[224:225], v[204:205], v[86:87], v[224:225]
	v_pk_fma_f32 v[226:227], v[206:207], v[86:87], v[226:227]
	v_cvt_pk_f32_fp8_sdwa v[208:209], v174 src0_sel:WORD_1
	v_cvt_pk_f32_fp8_sdwa v[210:211], v178 src0_sel:WORD_1
	v_pk_fma_f32 v[224:225], v[208:209], v[88:89], v[224:225]
	v_pk_fma_f32 v[226:227], v[210:211], v[88:89], v[226:227]
	v_cvt_pk_f32_fp8_e32 v[212:213], v175
	v_cvt_pk_f32_fp8_e32 v[214:215], v179
	v_pk_fma_f32 v[224:225], v[212:213], v[90:91], v[224:225]
	v_pk_fma_f32 v[226:227], v[214:215], v[90:91], v[226:227]
	v_cvt_pk_f32_fp8_sdwa v[216:217], v175 src0_sel:WORD_1
	v_cvt_pk_f32_fp8_sdwa v[218:219], v179 src0_sel:WORD_1
	v_pk_fma_f32 v[224:225], v[216:217], v[92:93], v[224:225]
	v_pk_fma_f32 v[226:227], v[218:219], v[92:93], v[226:227]
	v_add_f32_e32 v118, v220, v221
	v_add_f32_e32 v119, v222, v223
	v_add_f32_e32 v120, v224, v225
	v_add_f32_e32 v121, v226, v227
	v_add_f32_dpp v118, v118, v118 quad_perm:[1,0,3,2] row_mask:0xf bank_mask:0xf
	v_add_f32_dpp v119, v119, v119 quad_perm:[1,0,3,2] row_mask:0xf bank_mask:0xf
	v_add_f32_dpp v120, v120, v120 quad_perm:[1,0,3,2] row_mask:0xf bank_mask:0xf
	v_add_f32_dpp v121, v121, v121 quad_perm:[1,0,3,2] row_mask:0xf bank_mask:0xf
	v_add_f32_dpp v118, v118, v118 quad_perm:[2,3,0,1] row_mask:0xf bank_mask:0xf
	v_add_f32_dpp v119, v119, v119 quad_perm:[2,3,0,1] row_mask:0xf bank_mask:0xf
	v_add_f32_dpp v120, v120, v120 quad_perm:[2,3,0,1] row_mask:0xf bank_mask:0xf
	v_add_f32_dpp v121, v121, v121 quad_perm:[2,3,0,1] row_mask:0xf bank_mask:0xf
	v_add_f32_dpp v118, v118, v118 row_half_mirror row_mask:0xf bank_mask:0xf
	v_add_f32_dpp v119, v119, v119 row_half_mirror row_mask:0xf bank_mask:0xf
	v_add_f32_dpp v120, v120, v120 row_half_mirror row_mask:0xf bank_mask:0xf
	v_add_f32_dpp v121, v121, v121 row_half_mirror row_mask:0xf bank_mask:0xf
	s_waitcnt vmcnt(18)
	v_cvt_pk_f32_fp8_e32 v[204:205], v180
	v_cvt_pk_f32_fp8_e32 v[206:207], v184
	v_pk_mul_f32 v[220:221], v[204:205], v[78:79]
	v_pk_mul_f32 v[222:223], v[206:207], v[78:79]
	v_cvt_pk_f32_fp8_sdwa v[208:209], v180 src0_sel:WORD_1
	v_cvt_pk_f32_fp8_sdwa v[210:211], v184 src0_sel:WORD_1
	v_pk_fma_f32 v[220:221], v[208:209], v[80:81], v[220:221]
	v_pk_fma_f32 v[222:223], v[210:211], v[80:81], v[222:223]
	v_cvt_pk_f32_fp8_e32 v[212:213], v181
	v_cvt_pk_f32_fp8_e32 v[214:215], v185
	v_pk_fma_f32 v[220:221], v[212:213], v[82:83], v[220:221]
	v_pk_fma_f32 v[222:223], v[214:215], v[82:83], v[222:223]
	v_cvt_pk_f32_fp8_sdwa v[216:217], v181 src0_sel:WORD_1
	v_cvt_pk_f32_fp8_sdwa v[218:219], v185 src0_sel:WORD_1
	v_pk_fma_f32 v[220:221], v[216:217], v[84:85], v[220:221]
	v_pk_fma_f32 v[222:223], v[218:219], v[84:85], v[222:223]
	v_cvt_pk_f32_fp8_e32 v[204:205], v182
	v_cvt_pk_f32_fp8_e32 v[206:207], v186
	v_pk_fma_f32 v[220:221], v[204:205], v[86:87], v[220:221]
	v_pk_fma_f32 v[222:223], v[206:207], v[86:87], v[222:223]
	v_cvt_pk_f32_fp8_sdwa v[208:209], v182 src0_sel:WORD_1
	v_cvt_pk_f32_fp8_sdwa v[210:211], v186 src0_sel:WORD_1
	v_pk_fma_f32 v[220:221], v[208:209], v[88:89], v[220:221]
	v_pk_fma_f32 v[222:223], v[210:211], v[88:89], v[222:223]
	v_cvt_pk_f32_fp8_e32 v[212:213], v183
	v_cvt_pk_f32_fp8_e32 v[214:215], v187
	v_pk_fma_f32 v[220:221], v[212:213], v[90:91], v[220:221]
	v_pk_fma_f32 v[222:223], v[214:215], v[90:91], v[222:223]
	v_cvt_pk_f32_fp8_sdwa v[216:217], v183 src0_sel:WORD_1
	v_cvt_pk_f32_fp8_sdwa v[218:219], v187 src0_sel:WORD_1
	v_pk_fma_f32 v[220:221], v[216:217], v[92:93], v[220:221]
	v_pk_fma_f32 v[222:223], v[218:219], v[92:93], v[222:223]
	s_waitcnt vmcnt(16)
; __device__ __forceinline__ void attn_phase(const Args& a, unsigned char* lds, int lane, int wave) {
;     ...
;             for (int i = 0; i < 8; ++i) { float kf[16]; unpack16_fp8(kk[i], kf); float d0 = 0.f, d1 = 0.f;
; #pragma unroll
;                 for (int x = 0; x < 16; x += 2) { d0 += q[x] * kf[x]; d1 += q[x + 1] * kf[x + 1]; }
;                 float d = d0 + d1;
;                 d += __shfl_xor(d, 1); d += __shfl_xor(d, 2); d += __shfl_xor(d, 4); s[i] = d; }
;             const float mn = fmaxf(fmaxf(fmaxf(mx, fmaxf(s[0], s[1])), fmaxf(s[2], s[3])), fmaxf(fmaxf(s[4], s[5]), fmaxf(s[6], s[7])));
;             const float al = __builtin_amdgcn_exp2f(mx - mn);
;             float p[8];
; #pragma unroll
;             for (int i = 0; i < 8; ++i) p[i] = __builtin_amdgcn_exp2f(s[i] - mn);
;             l = l * al + ((p[0] + p[1]) + (p[2] + p[3])) + ((p[4] + p[5]) + (p[6] + p[7]));
; #pragma unroll
;             for (int d = 0; d < 16; ++d) o[d] *= al;
; #pragma unroll
;             for (int i = 0; i < 8; ++i) { float vf[16]; unpack16_fp8(vv[i], vf);
; #pragma unroll
;                 for (int d = 0; d < 16; ++d) o[d] += p[i] * vf[d]; }
	v_cvt_pk_f32_fp8_e32 v[204:205], v188
	v_cvt_pk_f32_fp8_e32 v[206:207], v192
	v_pk_mul_f32 v[224:225], v[204:205], v[78:79]
	v_pk_mul_f32 v[226:227], v[206:207], v[78:79]
	v_cvt_pk_f32_fp8_sdwa v[208:209], v188 src0_sel:WORD_1
	v_cvt_pk_f32_fp8_sdwa v[210:211], v192 src0_sel:WORD_1
	v_pk_fma_f32 v[224:225], v[208:209], v[80:81], v[224:225]
	v_pk_fma_f32 v[226:227], v[210:211], v[80:81], v[226:227]
	v_cvt_pk_f32_fp8_e32 v[212:213], v189
	v_cvt_pk_f32_fp8_e32 v[214:215], v193
	v_pk_fma_f32 v[224:225], v[212:213], v[82:83], v[224:225]
	v_pk_fma_f32 v[226:227], v[214:215], v[82:83], v[226:227]
	v_cvt_pk_f32_fp8_sdwa v[216:217], v189 src0_sel:WORD_1
	v_cvt_pk_f32_fp8_sdwa v[218:219], v193 src0_sel:WORD_1
	v_pk_fma_f32 v[224:225], v[216:217], v[84:85], v[224:225]
	v_pk_fma_f32 v[226:227], v[218:219], v[84:85], v[226:227]
	v_cvt_pk_f32_fp8_e32 v[204:205], v190
	v_cvt_pk_f32_fp8_e32 v[206:207], v194
	v_pk_fma_f32 v[224:225], v[204:205], v[86:87], v[224:225]
	v_pk_fma_f32 v[226:227], v[206:207], v[86:87], v[226:227]
	v_cvt_pk_f32_fp8_sdwa v[208:209], v190 src0_sel:WORD_1
	v_cvt_pk_f32_fp8_sdwa v[210:211], v194 src0_sel:WORD_1
	v_pk_fma_f32 v[224:225], v[208:209], v[88:89], v[224:225]
	v_pk_fma_f32 v[226:227], v[210:211], v[88:89], v[226:227]
	v_cvt_pk_f32_fp8_e32 v[212:213], v191
	v_cvt_pk_f32_fp8_e32 v[214:215], v195
	v_pk_fma_f32 v[224:225], v[212:213], v[90:91], v[224:225]
	v_pk_fma_f32 v[226:227], v[214:215], v[90:91], v[226:227]
	v_cvt_pk_f32_fp8_sdwa v[216:217], v191 src0_sel:WORD_1
	v_cvt_pk_f32_fp8_sdwa v[218:219], v195 src0_sel:WORD_1
	v_pk_fma_f32 v[224:225], v[216:217], v[92:93], v[224:225]
	v_pk_fma_f32 v[226:227], v[218:219], v[92:93], v[226:227]
	v_add_f32_e32 v122, v220, v221
	v_add_f32_e32 v123, v222, v223
	v_add_f32_e32 v124, v224, v225
	v_add_f32_e32 v125, v226, v227
	v_add_f32_dpp v122, v122, v122 quad_perm:[1,0,3,2] row_mask:0xf bank_mask:0xf
	v_add_f32_dpp v123, v123, v123 quad_perm:[1,0,3,2] row_mask:0xf bank_mask:0xf
	v_add_f32_dpp v124, v124, v124 quad_perm:[1,0,3,2] row_mask:0xf bank_mask:0xf
	v_add_f32_dpp v125, v125, v125 quad_perm:[1,0,3,2] row_mask:0xf bank_mask:0xf
	v_add_f32_dpp v122, v122, v122 quad_perm:[2,3,0,1] row_mask:0xf bank_mask:0xf
	v_add_f32_dpp v123, v123, v123 quad_perm:[2,3,0,1] row_mask:0xf bank_mask:0xf
	v_add_f32_dpp v124, v124, v124 quad_perm:[2,3,0,1] row_mask:0xf bank_mask:0xf
	v_add_f32_dpp v125, v125, v125 quad_perm:[2,3,0,1] row_mask:0xf bank_mask:0xf
	v_add_f32_dpp v122, v122, v122 row_half_mirror row_mask:0xf bank_mask:0xf
	v_add_f32_dpp v123, v123, v123 row_half_mirror row_mask:0xf bank_mask:0xf
	v_add_f32_dpp v124, v124, v124 row_half_mirror row_mask:0xf bank_mask:0xf
	v_add_f32_dpp v125, v125, v125 row_half_mirror row_mask:0xf bank_mask:0xf
	v_max3_f32 v228, v110, v111, v112
	v_max3_f32 v229, v113, v114, v115
	v_max3_f32 v230, v116, v117, v118
	v_max3_f32 v231, v119, v120, v121
	v_max3_f32 v232, v122, v123, v124
	v_max3_f32 v233, v125, v109, v228
	v_max3_f32 v234, v229, v230, v231
	v_max3_f32 v235, v232, v233, v234
	v_sub_f32_e32 v236, v109, v235
	v_sub_f32_e32 v110, v110, v235
	v_sub_f32_e32 v111, v111, v235
	v_sub_f32_e32 v112, v112, v235
	v_sub_f32_e32 v113, v113, v235
	v_sub_f32_e32 v114, v114, v235
	v_sub_f32_e32 v115, v115, v235
	v_sub_f32_e32 v116, v116, v235
	v_sub_f32_e32 v117, v117, v235
	v_sub_f32_e32 v118, v118, v235
	v_sub_f32_e32 v119, v119, v235
	v_sub_f32_e32 v120, v120, v235
	v_sub_f32_e32 v121, v121, v235
	v_sub_f32_e32 v122, v122, v235
	v_sub_f32_e32 v123, v123, v235
	v_sub_f32_e32 v124, v124, v235
	v_sub_f32_e32 v125, v125, v235
	v_exp_f32_e32 v244, v236
	v_exp_f32_e32 v110, v110
	v_exp_f32_e32 v111, v111
	v_exp_f32_e32 v112, v112
	v_exp_f32_e32 v113, v113
	v_exp_f32_e32 v114, v114
	v_exp_f32_e32 v115, v115
	v_exp_f32_e32 v116, v116
	v_exp_f32_e32 v117, v117
	v_exp_f32_e32 v118, v118
	v_exp_f32_e32 v119, v119
	v_exp_f32_e32 v120, v120
	v_exp_f32_e32 v121, v121
	v_exp_f32_e32 v122, v122
	v_exp_f32_e32 v123, v123
	v_exp_f32_e32 v124, v124
	v_exp_f32_e32 v125, v125
	v_mov_b32_e32 v109, v235
	v_pk_mul_f32 v[62:63], v[62:63], v[244:245] op_sel_hi:[1,0]
	v_pk_mul_f32 v[64:65], v[64:65], v[244:245] op_sel_hi:[1,0]
	v_pk_mul_f32 v[66:67], v[66:67], v[244:245] op_sel_hi:[1,0]
	v_pk_mul_f32 v[68:69], v[68:69], v[244:245] op_sel_hi:[1,0]
	v_pk_mul_f32 v[70:71], v[70:71], v[244:245] op_sel_hi:[1,0]
	v_pk_mul_f32 v[72:73], v[72:73], v[244:245] op_sel_hi:[1,0]
	v_pk_mul_f32 v[74:75], v[74:75], v[244:245] op_sel_hi:[1,0]
	v_pk_mul_f32 v[76:77], v[76:77], v[244:245] op_sel_hi:[1,0]
	v_add_f32_e32 v228, v110, v111
	v_add_f32_e32 v229, v112, v113
	v_add_f32_e32 v230, v114, v115
	v_add_f32_e32 v231, v116, v117
	v_add_f32_e32 v232, v118, v119
	v_add_f32_e32 v233, v120, v121
	v_add_f32_e32 v234, v122, v123
	v_add_f32_e32 v235, v124, v125
	v_add_f32_e32 v228, v228, v229
	v_add_f32_e32 v230, v230, v231
	v_add_f32_e32 v232, v232, v233
	v_add_f32_e32 v234, v234, v235
	v_add_f32_e32 v228, v228, v230
	v_add_f32_e32 v232, v232, v234
	v_add_f32_e32 v228, v228, v232
	v_fma_f32 v108, v108, v244, v228
	s_waitcnt vmcnt(15)
	v_cvt_pk_f32_fp8_e32 v[204:205], v0
	v_cvt_pk_f32_fp8_sdwa v[206:207], v0 src0_sel:WORD_1
	v_pk_fma_f32 v[62:63], v[204:205], v[110:111], v[62:63] op_sel_hi:[1,0,1]
	v_pk_fma_f32 v[64:65], v[206:207], v[110:111], v[64:65] op_sel_hi:[1,0,1]
	v_cvt_pk_f32_fp8_e32 v[208:209], v1
	v_cvt_pk_f32_fp8_sdwa v[210:211], v1 src0_sel:WORD_1
	v_pk_fma_f32 v[66:67], v[208:209], v[110:111], v[66:67] op_sel_hi:[1,0,1]
	v_pk_fma_f32 v[68:69], v[210:211], v[110:111], v[68:69] op_sel_hi:[1,0,1]
	v_cvt_pk_f32_fp8_e32 v[212:213], v2
	v_cvt_pk_f32_fp8_sdwa v[214:215], v2 src0_sel:WORD_1
	v_pk_fma_f32 v[70:71], v[212:213], v[110:111], v[70:71] op_sel_hi:[1,0,1]
	v_pk_fma_f32 v[72:73], v[214:215], v[110:111], v[72:73] op_sel_hi:[1,0,1]
	v_cvt_pk_f32_fp8_e32 v[216:217], v3
	v_cvt_pk_f32_fp8_sdwa v[218:219], v3 src0_sel:WORD_1
	v_pk_fma_f32 v[74:75], v[216:217], v[110:111], v[74:75] op_sel_hi:[1,0,1]
	v_pk_fma_f32 v[76:77], v[218:219], v[110:111], v[76:77] op_sel_hi:[1,0,1]
	s_waitcnt vmcnt(14)
; __device__ __forceinline__ void attn_phase(const Args& a, unsigned char* lds, int lane, int wave) {
;     ...
;             for (int i = 0; i < 8; ++i) { float vf[16]; unpack16_fp8(vv[i], vf);
; #pragma unroll
;                 for (int d = 0; d < 16; ++d) o[d] += p[i] * vf[d]; }
	v_cvt_pk_f32_fp8_e32 v[204:205], v4
	v_cvt_pk_f32_fp8_sdwa v[206:207], v4 src0_sel:WORD_1
	v_pk_fma_f32 v[62:63], v[204:205], v[110:111], v[62:63] op_sel:[0,1,0] op_sel_hi:[1,1,1]
	v_pk_fma_f32 v[64:65], v[206:207], v[110:111], v[64:65] op_sel:[0,1,0] op_sel_hi:[1,1,1]
	v_cvt_pk_f32_fp8_e32 v[208:209], v5
	v_cvt_pk_f32_fp8_sdwa v[210:211], v5 src0_sel:WORD_1
	v_pk_fma_f32 v[66:67], v[208:209], v[110:111], v[66:67] op_sel:[0,1,0] op_sel_hi:[1,1,1]
	v_pk_fma_f32 v[68:69], v[210:211], v[110:111], v[68:69] op_sel:[0,1,0] op_sel_hi:[1,1,1]
	v_cvt_pk_f32_fp8_e32 v[212:213], v6
	v_cvt_pk_f32_fp8_sdwa v[214:215], v6 src0_sel:WORD_1
	v_pk_fma_f32 v[70:71], v[212:213], v[110:111], v[70:71] op_sel:[0,1,0] op_sel_hi:[1,1,1]
	v_pk_fma_f32 v[72:73], v[214:215], v[110:111], v[72:73] op_sel:[0,1,0] op_sel_hi:[1,1,1]
	v_cvt_pk_f32_fp8_e32 v[216:217], v7
	v_cvt_pk_f32_fp8_sdwa v[218:219], v7 src0_sel:WORD_1
	v_pk_fma_f32 v[74:75], v[216:217], v[110:111], v[74:75] op_sel:[0,1,0] op_sel_hi:[1,1,1]
	v_pk_fma_f32 v[76:77], v[218:219], v[110:111], v[76:77] op_sel:[0,1,0] op_sel_hi:[1,1,1]
	s_waitcnt vmcnt(13)
	v_cvt_pk_f32_fp8_e32 v[204:205], v8
	v_cvt_pk_f32_fp8_sdwa v[206:207], v8 src0_sel:WORD_1
	v_pk_fma_f32 v[62:63], v[204:205], v[112:113], v[62:63] op_sel_hi:[1,0,1]
	v_pk_fma_f32 v[64:65], v[206:207], v[112:113], v[64:65] op_sel_hi:[1,0,1]
	v_cvt_pk_f32_fp8_e32 v[208:209], v9
	v_cvt_pk_f32_fp8_sdwa v[210:211], v9 src0_sel:WORD_1
	v_pk_fma_f32 v[66:67], v[208:209], v[112:113], v[66:67] op_sel_hi:[1,0,1]
	v_pk_fma_f32 v[68:69], v[210:211], v[112:113], v[68:69] op_sel_hi:[1,0,1]
	v_cvt_pk_f32_fp8_e32 v[212:213], v10
	v_cvt_pk_f32_fp8_sdwa v[214:215], v10 src0_sel:WORD_1
	v_pk_fma_f32 v[70:71], v[212:213], v[112:113], v[70:71] op_sel_hi:[1,0,1]
	v_pk_fma_f32 v[72:73], v[214:215], v[112:113], v[72:73] op_sel_hi:[1,0,1]
	v_cvt_pk_f32_fp8_e32 v[216:217], v11
	v_cvt_pk_f32_fp8_sdwa v[218:219], v11 src0_sel:WORD_1
	v_pk_fma_f32 v[74:75], v[216:217], v[112:113], v[74:75] op_sel_hi:[1,0,1]
	v_pk_fma_f32 v[76:77], v[218:219], v[112:113], v[76:77] op_sel_hi:[1,0,1]
	s_waitcnt vmcnt(12)
	v_cvt_pk_f32_fp8_e32 v[204:205], v12
	v_cvt_pk_f32_fp8_sdwa v[206:207], v12 src0_sel:WORD_1
	v_pk_fma_f32 v[62:63], v[204:205], v[112:113], v[62:63] op_sel:[0,1,0] op_sel_hi:[1,1,1]
	v_pk_fma_f32 v[64:65], v[206:207], v[112:113], v[64:65] op_sel:[0,1,0] op_sel_hi:[1,1,1]
	v_cvt_pk_f32_fp8_e32 v[208:209], v13
	v_cvt_pk_f32_fp8_sdwa v[210:211], v13 src0_sel:WORD_1
	v_pk_fma_f32 v[66:67], v[208:209], v[112:113], v[66:67] op_sel:[0,1,0] op_sel_hi:[1,1,1]
	v_pk_fma_f32 v[68:69], v[210:211], v[112:113], v[68:69] op_sel:[0,1,0] op_sel_hi:[1,1,1]
	v_cvt_pk_f32_fp8_e32 v[212:213], v14
	v_cvt_pk_f32_fp8_sdwa v[214:215], v14 src0_sel:WORD_1
	v_pk_fma_f32 v[70:71], v[212:213], v[112:113], v[70:71] op_sel:[0,1,0] op_sel_hi:[1,1,1]
	v_pk_fma_f32 v[72:73], v[214:215], v[112:113], v[72:73] op_sel:[0,1,0] op_sel_hi:[1,1,1]
	v_cvt_pk_f32_fp8_e32 v[216:217], v15
	v_cvt_pk_f32_fp8_sdwa v[218:219], v15 src0_sel:WORD_1
	v_pk_fma_f32 v[74:75], v[216:217], v[112:113], v[74:75] op_sel:[0,1,0] op_sel_hi:[1,1,1]
	v_pk_fma_f32 v[76:77], v[218:219], v[112:113], v[76:77] op_sel:[0,1,0] op_sel_hi:[1,1,1]
	s_waitcnt vmcnt(11)
	v_cvt_pk_f32_fp8_e32 v[204:205], v16
	v_cvt_pk_f32_fp8_sdwa v[206:207], v16 src0_sel:WORD_1
	v_pk_fma_f32 v[62:63], v[204:205], v[114:115], v[62:63] op_sel_hi:[1,0,1]
	v_pk_fma_f32 v[64:65], v[206:207], v[114:115], v[64:65] op_sel_hi:[1,0,1]
	v_cvt_pk_f32_fp8_e32 v[208:209], v17
	v_cvt_pk_f32_fp8_sdwa v[210:211], v17 src0_sel:WORD_1
	v_pk_fma_f32 v[66:67], v[208:209], v[114:115], v[66:67] op_sel_hi:[1,0,1]
	v_pk_fma_f32 v[68:69], v[210:211], v[114:115], v[68:69] op_sel_hi:[1,0,1]
	v_cvt_pk_f32_fp8_e32 v[212:213], v18
	v_cvt_pk_f32_fp8_sdwa v[214:215], v18 src0_sel:WORD_1
	v_pk_fma_f32 v[70:71], v[212:213], v[114:115], v[70:71] op_sel_hi:[1,0,1]
	v_pk_fma_f32 v[72:73], v[214:215], v[114:115], v[72:73] op_sel_hi:[1,0,1]
	v_cvt_pk_f32_fp8_e32 v[216:217], v19
	v_cvt_pk_f32_fp8_sdwa v[218:219], v19 src0_sel:WORD_1
	v_pk_fma_f32 v[74:75], v[216:217], v[114:115], v[74:75] op_sel_hi:[1,0,1]
	v_pk_fma_f32 v[76:77], v[218:219], v[114:115], v[76:77] op_sel_hi:[1,0,1]
	s_waitcnt vmcnt(10)
	v_cvt_pk_f32_fp8_e32 v[204:205], v20
	v_cvt_pk_f32_fp8_sdwa v[206:207], v20 src0_sel:WORD_1
	v_pk_fma_f32 v[62:63], v[204:205], v[114:115], v[62:63] op_sel:[0,1,0] op_sel_hi:[1,1,1]
	v_pk_fma_f32 v[64:65], v[206:207], v[114:115], v[64:65] op_sel:[0,1,0] op_sel_hi:[1,1,1]
	v_cvt_pk_f32_fp8_e32 v[208:209], v21
	v_cvt_pk_f32_fp8_sdwa v[210:211], v21 src0_sel:WORD_1
	v_pk_fma_f32 v[66:67], v[208:209], v[114:115], v[66:67] op_sel:[0,1,0] op_sel_hi:[1,1,1]
	v_pk_fma_f32 v[68:69], v[210:211], v[114:115], v[68:69] op_sel:[0,1,0] op_sel_hi:[1,1,1]
	v_cvt_pk_f32_fp8_e32 v[212:213], v22
	v_cvt_pk_f32_fp8_sdwa v[214:215], v22 src0_sel:WORD_1
	v_pk_fma_f32 v[70:71], v[212:213], v[114:115], v[70:71] op_sel:[0,1,0] op_sel_hi:[1,1,1]
	v_pk_fma_f32 v[72:73], v[214:215], v[114:115], v[72:73] op_sel:[0,1,0] op_sel_hi:[1,1,1]
	v_cvt_pk_f32_fp8_e32 v[216:217], v23
	v_cvt_pk_f32_fp8_sdwa v[218:219], v23 src0_sel:WORD_1
	v_pk_fma_f32 v[74:75], v[216:217], v[114:115], v[74:75] op_sel:[0,1,0] op_sel_hi:[1,1,1]
	v_pk_fma_f32 v[76:77], v[218:219], v[114:115], v[76:77] op_sel:[0,1,0] op_sel_hi:[1,1,1]
	s_waitcnt vmcnt(9)
; __device__ __forceinline__ void attn_phase(const Args& a, unsigned char* lds, int lane, int wave) {
;     ...
;             for (int i = 0; i < 8; ++i) { float vf[16]; unpack16_fp8(vv[i], vf);
; #pragma unroll
;                 for (int d = 0; d < 16; ++d) o[d] += p[i] * vf[d]; }
	v_cvt_pk_f32_fp8_e32 v[204:205], v24
	v_cvt_pk_f32_fp8_sdwa v[206:207], v24 src0_sel:WORD_1
	v_pk_fma_f32 v[62:63], v[204:205], v[116:117], v[62:63] op_sel_hi:[1,0,1]
	v_pk_fma_f32 v[64:65], v[206:207], v[116:117], v[64:65] op_sel_hi:[1,0,1]
	v_cvt_pk_f32_fp8_e32 v[208:209], v25
	v_cvt_pk_f32_fp8_sdwa v[210:211], v25 src0_sel:WORD_1
	v_pk_fma_f32 v[66:67], v[208:209], v[116:117], v[66:67] op_sel_hi:[1,0,1]
	v_pk_fma_f32 v[68:69], v[210:211], v[116:117], v[68:69] op_sel_hi:[1,0,1]
	v_cvt_pk_f32_fp8_e32 v[212:213], v26
	v_cvt_pk_f32_fp8_sdwa v[214:215], v26 src0_sel:WORD_1
	v_pk_fma_f32 v[70:71], v[212:213], v[116:117], v[70:71] op_sel_hi:[1,0,1]
	v_pk_fma_f32 v[72:73], v[214:215], v[116:117], v[72:73] op_sel_hi:[1,0,1]
	v_cvt_pk_f32_fp8_e32 v[216:217], v27
	v_cvt_pk_f32_fp8_sdwa v[218:219], v27 src0_sel:WORD_1
	v_pk_fma_f32 v[74:75], v[216:217], v[116:117], v[74:75] op_sel_hi:[1,0,1]
	v_pk_fma_f32 v[76:77], v[218:219], v[116:117], v[76:77] op_sel_hi:[1,0,1]
	s_waitcnt vmcnt(8)
	v_cvt_pk_f32_fp8_e32 v[204:205], v28
	v_cvt_pk_f32_fp8_sdwa v[206:207], v28 src0_sel:WORD_1
	v_pk_fma_f32 v[62:63], v[204:205], v[116:117], v[62:63] op_sel:[0,1,0] op_sel_hi:[1,1,1]
	v_pk_fma_f32 v[64:65], v[206:207], v[116:117], v[64:65] op_sel:[0,1,0] op_sel_hi:[1,1,1]
	v_cvt_pk_f32_fp8_e32 v[208:209], v29
	v_cvt_pk_f32_fp8_sdwa v[210:211], v29 src0_sel:WORD_1
	v_pk_fma_f32 v[66:67], v[208:209], v[116:117], v[66:67] op_sel:[0,1,0] op_sel_hi:[1,1,1]
	v_pk_fma_f32 v[68:69], v[210:211], v[116:117], v[68:69] op_sel:[0,1,0] op_sel_hi:[1,1,1]
	v_cvt_pk_f32_fp8_e32 v[212:213], v30
	v_cvt_pk_f32_fp8_sdwa v[214:215], v30 src0_sel:WORD_1
	v_pk_fma_f32 v[70:71], v[212:213], v[116:117], v[70:71] op_sel:[0,1,0] op_sel_hi:[1,1,1]
	v_pk_fma_f32 v[72:73], v[214:215], v[116:117], v[72:73] op_sel:[0,1,0] op_sel_hi:[1,1,1]
	v_cvt_pk_f32_fp8_e32 v[216:217], v31
	v_cvt_pk_f32_fp8_sdwa v[218:219], v31 src0_sel:WORD_1
	v_pk_fma_f32 v[74:75], v[216:217], v[116:117], v[74:75] op_sel:[0,1,0] op_sel_hi:[1,1,1]
	v_pk_fma_f32 v[76:77], v[218:219], v[116:117], v[76:77] op_sel:[0,1,0] op_sel_hi:[1,1,1]
	s_waitcnt vmcnt(7)
	v_cvt_pk_f32_fp8_e32 v[204:205], v32
	v_cvt_pk_f32_fp8_sdwa v[206:207], v32 src0_sel:WORD_1
	v_pk_fma_f32 v[62:63], v[204:205], v[118:119], v[62:63] op_sel_hi:[1,0,1]
	v_pk_fma_f32 v[64:65], v[206:207], v[118:119], v[64:65] op_sel_hi:[1,0,1]
	v_cvt_pk_f32_fp8_e32 v[208:209], v33
	v_cvt_pk_f32_fp8_sdwa v[210:211], v33 src0_sel:WORD_1
	v_pk_fma_f32 v[66:67], v[208:209], v[118:119], v[66:67] op_sel_hi:[1,0,1]
	v_pk_fma_f32 v[68:69], v[210:211], v[118:119], v[68:69] op_sel_hi:[1,0,1]
	v_cvt_pk_f32_fp8_e32 v[212:213], v34
	v_cvt_pk_f32_fp8_sdwa v[214:215], v34 src0_sel:WORD_1
	v_pk_fma_f32 v[70:71], v[212:213], v[118:119], v[70:71] op_sel_hi:[1,0,1]
	v_pk_fma_f32 v[72:73], v[214:215], v[118:119], v[72:73] op_sel_hi:[1,0,1]
	v_cvt_pk_f32_fp8_e32 v[216:217], v35
	v_cvt_pk_f32_fp8_sdwa v[218:219], v35 src0_sel:WORD_1
	v_pk_fma_f32 v[74:75], v[216:217], v[118:119], v[74:75] op_sel_hi:[1,0,1]
	v_pk_fma_f32 v[76:77], v[218:219], v[118:119], v[76:77] op_sel_hi:[1,0,1]
	s_waitcnt vmcnt(6)
	v_cvt_pk_f32_fp8_e32 v[204:205], v36
	v_cvt_pk_f32_fp8_sdwa v[206:207], v36 src0_sel:WORD_1
	v_pk_fma_f32 v[62:63], v[204:205], v[118:119], v[62:63] op_sel:[0,1,0] op_sel_hi:[1,1,1]
	v_pk_fma_f32 v[64:65], v[206:207], v[118:119], v[64:65] op_sel:[0,1,0] op_sel_hi:[1,1,1]
	v_cvt_pk_f32_fp8_e32 v[208:209], v37
	v_cvt_pk_f32_fp8_sdwa v[210:211], v37 src0_sel:WORD_1
	v_pk_fma_f32 v[66:67], v[208:209], v[118:119], v[66:67] op_sel:[0,1,0] op_sel_hi:[1,1,1]
	v_pk_fma_f32 v[68:69], v[210:211], v[118:119], v[68:69] op_sel:[0,1,0] op_sel_hi:[1,1,1]
	v_cvt_pk_f32_fp8_e32 v[212:213], v38
	v_cvt_pk_f32_fp8_sdwa v[214:215], v38 src0_sel:WORD_1
	v_pk_fma_f32 v[70:71], v[212:213], v[118:119], v[70:71] op_sel:[0,1,0] op_sel_hi:[1,1,1]
	v_pk_fma_f32 v[72:73], v[214:215], v[118:119], v[72:73] op_sel:[0,1,0] op_sel_hi:[1,1,1]
	v_cvt_pk_f32_fp8_e32 v[216:217], v39
	v_cvt_pk_f32_fp8_sdwa v[218:219], v39 src0_sel:WORD_1
	v_pk_fma_f32 v[74:75], v[216:217], v[118:119], v[74:75] op_sel:[0,1,0] op_sel_hi:[1,1,1]
	v_pk_fma_f32 v[76:77], v[218:219], v[118:119], v[76:77] op_sel:[0,1,0] op_sel_hi:[1,1,1]
	s_waitcnt vmcnt(5)
	v_cvt_pk_f32_fp8_e32 v[204:205], v40
	v_cvt_pk_f32_fp8_sdwa v[206:207], v40 src0_sel:WORD_1
	v_pk_fma_f32 v[62:63], v[204:205], v[120:121], v[62:63] op_sel_hi:[1,0,1]
	v_pk_fma_f32 v[64:65], v[206:207], v[120:121], v[64:65] op_sel_hi:[1,0,1]
	v_cvt_pk_f32_fp8_e32 v[208:209], v41
	v_cvt_pk_f32_fp8_sdwa v[210:211], v41 src0_sel:WORD_1
	v_pk_fma_f32 v[66:67], v[208:209], v[120:121], v[66:67] op_sel_hi:[1,0,1]
	v_pk_fma_f32 v[68:69], v[210:211], v[120:121], v[68:69] op_sel_hi:[1,0,1]
	v_cvt_pk_f32_fp8_e32 v[212:213], v42
	v_cvt_pk_f32_fp8_sdwa v[214:215], v42 src0_sel:WORD_1
	v_pk_fma_f32 v[70:71], v[212:213], v[120:121], v[70:71] op_sel_hi:[1,0,1]
	v_pk_fma_f32 v[72:73], v[214:215], v[120:121], v[72:73] op_sel_hi:[1,0,1]
	v_cvt_pk_f32_fp8_e32 v[216:217], v43
	v_cvt_pk_f32_fp8_sdwa v[218:219], v43 src0_sel:WORD_1
	v_pk_fma_f32 v[74:75], v[216:217], v[120:121], v[74:75] op_sel_hi:[1,0,1]
	v_pk_fma_f32 v[76:77], v[218:219], v[120:121], v[76:77] op_sel_hi:[1,0,1]
	s_waitcnt vmcnt(4)
; __device__ __forceinline__ u32x4 pack8(const float* v) { u32x4 w; w.x = pk2(v[0], v[1]); w.y = pk2(v[2], v[3]); w.z = pk2(v[4], v[5]); w.w = pk2(v[6], v[7]); return w; }
; __device__ __forceinline__ void attn_phase(const Args& a, unsigned char* lds, int lane, int wave) {
;     ...
;             for (int i = 0; i < 8; ++i) { float vf[16]; unpack16_fp8(vv[i], vf);
; #pragma unroll
;                 for (int d = 0; d < 16; ++d) o[d] += p[i] * vf[d]; }
;             mx = mn;
;         }
;         const float il = 1.f / l;
; #pragma unroll
;         for (int d = 0; d < 16; ++d) o[d] *= il;
;         *(u32x4*)qp = pack8(o); *(u32x4*)(qp + 8) = pack8(o + 8);
;     }
	v_cvt_pk_f32_fp8_e32 v[204:205], v44
	v_cvt_pk_f32_fp8_sdwa v[206:207], v44 src0_sel:WORD_1
	v_pk_fma_f32 v[62:63], v[204:205], v[120:121], v[62:63] op_sel:[0,1,0] op_sel_hi:[1,1,1]
	v_pk_fma_f32 v[64:65], v[206:207], v[120:121], v[64:65] op_sel:[0,1,0] op_sel_hi:[1,1,1]
	v_cvt_pk_f32_fp8_e32 v[208:209], v45
	v_cvt_pk_f32_fp8_sdwa v[210:211], v45 src0_sel:WORD_1
	v_pk_fma_f32 v[66:67], v[208:209], v[120:121], v[66:67] op_sel:[0,1,0] op_sel_hi:[1,1,1]
	v_pk_fma_f32 v[68:69], v[210:211], v[120:121], v[68:69] op_sel:[0,1,0] op_sel_hi:[1,1,1]
	v_cvt_pk_f32_fp8_e32 v[212:213], v46
	v_cvt_pk_f32_fp8_sdwa v[214:215], v46 src0_sel:WORD_1
	v_pk_fma_f32 v[70:71], v[212:213], v[120:121], v[70:71] op_sel:[0,1,0] op_sel_hi:[1,1,1]
	v_pk_fma_f32 v[72:73], v[214:215], v[120:121], v[72:73] op_sel:[0,1,0] op_sel_hi:[1,1,1]
	v_cvt_pk_f32_fp8_e32 v[216:217], v47
	v_cvt_pk_f32_fp8_sdwa v[218:219], v47 src0_sel:WORD_1
	v_pk_fma_f32 v[74:75], v[216:217], v[120:121], v[74:75] op_sel:[0,1,0] op_sel_hi:[1,1,1]
	v_pk_fma_f32 v[76:77], v[218:219], v[120:121], v[76:77] op_sel:[0,1,0] op_sel_hi:[1,1,1]
	s_waitcnt vmcnt(3)
	v_cvt_pk_f32_fp8_e32 v[204:205], v48
	v_cvt_pk_f32_fp8_sdwa v[206:207], v48 src0_sel:WORD_1
	v_pk_fma_f32 v[62:63], v[204:205], v[122:123], v[62:63] op_sel_hi:[1,0,1]
	v_pk_fma_f32 v[64:65], v[206:207], v[122:123], v[64:65] op_sel_hi:[1,0,1]
	v_cvt_pk_f32_fp8_e32 v[208:209], v49
	v_cvt_pk_f32_fp8_sdwa v[210:211], v49 src0_sel:WORD_1
	v_pk_fma_f32 v[66:67], v[208:209], v[122:123], v[66:67] op_sel_hi:[1,0,1]
	v_pk_fma_f32 v[68:69], v[210:211], v[122:123], v[68:69] op_sel_hi:[1,0,1]
	v_cvt_pk_f32_fp8_e32 v[212:213], v50
	v_cvt_pk_f32_fp8_sdwa v[214:215], v50 src0_sel:WORD_1
	v_pk_fma_f32 v[70:71], v[212:213], v[122:123], v[70:71] op_sel_hi:[1,0,1]
	v_pk_fma_f32 v[72:73], v[214:215], v[122:123], v[72:73] op_sel_hi:[1,0,1]
	v_cvt_pk_f32_fp8_e32 v[216:217], v51
	v_cvt_pk_f32_fp8_sdwa v[218:219], v51 src0_sel:WORD_1
	v_pk_fma_f32 v[74:75], v[216:217], v[122:123], v[74:75] op_sel_hi:[1,0,1]
	v_pk_fma_f32 v[76:77], v[218:219], v[122:123], v[76:77] op_sel_hi:[1,0,1]
	s_waitcnt vmcnt(2)
	v_cvt_pk_f32_fp8_e32 v[204:205], v52
	v_cvt_pk_f32_fp8_sdwa v[206:207], v52 src0_sel:WORD_1
	v_pk_fma_f32 v[62:63], v[204:205], v[122:123], v[62:63] op_sel:[0,1,0] op_sel_hi:[1,1,1]
	v_pk_fma_f32 v[64:65], v[206:207], v[122:123], v[64:65] op_sel:[0,1,0] op_sel_hi:[1,1,1]
	v_cvt_pk_f32_fp8_e32 v[208:209], v53
	v_cvt_pk_f32_fp8_sdwa v[210:211], v53 src0_sel:WORD_1
	v_pk_fma_f32 v[66:67], v[208:209], v[122:123], v[66:67] op_sel:[0,1,0] op_sel_hi:[1,1,1]
	v_pk_fma_f32 v[68:69], v[210:211], v[122:123], v[68:69] op_sel:[0,1,0] op_sel_hi:[1,1,1]
	v_cvt_pk_f32_fp8_e32 v[212:213], v54
	v_cvt_pk_f32_fp8_sdwa v[214:215], v54 src0_sel:WORD_1
	v_pk_fma_f32 v[70:71], v[212:213], v[122:123], v[70:71] op_sel:[0,1,0] op_sel_hi:[1,1,1]
	v_pk_fma_f32 v[72:73], v[214:215], v[122:123], v[72:73] op_sel:[0,1,0] op_sel_hi:[1,1,1]
	v_cvt_pk_f32_fp8_e32 v[216:217], v55
	v_cvt_pk_f32_fp8_sdwa v[218:219], v55 src0_sel:WORD_1
	v_pk_fma_f32 v[74:75], v[216:217], v[122:123], v[74:75] op_sel:[0,1,0] op_sel_hi:[1,1,1]
	v_pk_fma_f32 v[76:77], v[218:219], v[122:123], v[76:77] op_sel:[0,1,0] op_sel_hi:[1,1,1]
	s_waitcnt vmcnt(1)
	v_cvt_pk_f32_fp8_e32 v[204:205], v196
	v_cvt_pk_f32_fp8_sdwa v[206:207], v196 src0_sel:WORD_1
	v_pk_fma_f32 v[62:63], v[204:205], v[124:125], v[62:63] op_sel_hi:[1,0,1]
	v_pk_fma_f32 v[64:65], v[206:207], v[124:125], v[64:65] op_sel_hi:[1,0,1]
	v_cvt_pk_f32_fp8_e32 v[208:209], v197
	v_cvt_pk_f32_fp8_sdwa v[210:211], v197 src0_sel:WORD_1
	v_pk_fma_f32 v[66:67], v[208:209], v[124:125], v[66:67] op_sel_hi:[1,0,1]
	v_pk_fma_f32 v[68:69], v[210:211], v[124:125], v[68:69] op_sel_hi:[1,0,1]
	v_cvt_pk_f32_fp8_e32 v[212:213], v198
	v_cvt_pk_f32_fp8_sdwa v[214:215], v198 src0_sel:WORD_1
	v_pk_fma_f32 v[70:71], v[212:213], v[124:125], v[70:71] op_sel_hi:[1,0,1]
	v_pk_fma_f32 v[72:73], v[214:215], v[124:125], v[72:73] op_sel_hi:[1,0,1]
	v_cvt_pk_f32_fp8_e32 v[216:217], v199
	v_cvt_pk_f32_fp8_sdwa v[218:219], v199 src0_sel:WORD_1
	v_pk_fma_f32 v[74:75], v[216:217], v[124:125], v[74:75] op_sel_hi:[1,0,1]
	v_pk_fma_f32 v[76:77], v[218:219], v[124:125], v[76:77] op_sel_hi:[1,0,1]
	s_waitcnt vmcnt(0)
	v_cvt_pk_f32_fp8_e32 v[204:205], v200
	v_cvt_pk_f32_fp8_sdwa v[206:207], v200 src0_sel:WORD_1
	v_pk_fma_f32 v[62:63], v[204:205], v[124:125], v[62:63] op_sel:[0,1,0] op_sel_hi:[1,1,1]
	v_pk_fma_f32 v[64:65], v[206:207], v[124:125], v[64:65] op_sel:[0,1,0] op_sel_hi:[1,1,1]
	v_cvt_pk_f32_fp8_e32 v[208:209], v201
	v_cvt_pk_f32_fp8_sdwa v[210:211], v201 src0_sel:WORD_1
	v_pk_fma_f32 v[66:67], v[208:209], v[124:125], v[66:67] op_sel:[0,1,0] op_sel_hi:[1,1,1]
	v_pk_fma_f32 v[68:69], v[210:211], v[124:125], v[68:69] op_sel:[0,1,0] op_sel_hi:[1,1,1]
	v_cvt_pk_f32_fp8_e32 v[212:213], v202
	v_cvt_pk_f32_fp8_sdwa v[214:215], v202 src0_sel:WORD_1
	v_pk_fma_f32 v[70:71], v[212:213], v[124:125], v[70:71] op_sel:[0,1,0] op_sel_hi:[1,1,1]
	v_pk_fma_f32 v[72:73], v[214:215], v[124:125], v[72:73] op_sel:[0,1,0] op_sel_hi:[1,1,1]
	v_cvt_pk_f32_fp8_e32 v[216:217], v203
	v_cvt_pk_f32_fp8_sdwa v[218:219], v203 src0_sel:WORD_1
	v_pk_fma_f32 v[74:75], v[216:217], v[124:125], v[74:75] op_sel:[0,1,0] op_sel_hi:[1,1,1]
	v_pk_fma_f32 v[76:77], v[218:219], v[124:125], v[76:77] op_sel:[0,1,0] op_sel_hi:[1,1,1]
	v_div_scale_f32 v0, s[0:1], v108, v108, 1.0
	v_rcp_f32_e32 v1, v0
	v_div_scale_f32 v2, vcc, 1.0, v108, 1.0
	s_add_i32 s2, s2, s28
	v_fma_f32 v3, -v0, v1, 1.0
	v_fmac_f32_e32 v1, v3, v1
	v_mul_f32_e32 v3, v2, v1
	v_fma_f32 v4, -v0, v3, v2
	v_fmac_f32_e32 v3, v4, v1
	v_fma_f32 v0, -v0, v3, v2
	v_div_fmas_f32 v0, v0, v1, v3
	v_div_fixup_f32 v0, v0, v108, 1.0
	v_pk_mul_f32 v[62:63], v[62:63], v[0:1] op_sel_hi:[1,0]
	v_pk_mul_f32 v[64:65], v[64:65], v[0:1] op_sel_hi:[1,0]
	v_pk_mul_f32 v[66:67], v[66:67], v[0:1] op_sel_hi:[1,0]
	v_pk_mul_f32 v[68:69], v[68:69], v[0:1] op_sel_hi:[1,0]
	v_pk_mul_f32 v[70:71], v[70:71], v[0:1] op_sel_hi:[1,0]
	v_pk_mul_f32 v[72:73], v[72:73], v[0:1] op_sel_hi:[1,0]
	v_pk_mul_f32 v[74:75], v[74:75], v[0:1] op_sel_hi:[1,0]
	v_pk_mul_f32 v[76:77], v[76:77], v[0:1] op_sel_hi:[1,0]
	v_cvt_pk_bf16_f32 v4, v62, v63
	v_cvt_pk_bf16_f32 v5, v64, v65
	v_cvt_pk_bf16_f32 v6, v66, v67
	v_cvt_pk_bf16_f32 v7, v68, v69
	v_cvt_pk_bf16_f32 v8, v70, v71
	v_cvt_pk_bf16_f32 v9, v72, v73
	v_cvt_pk_bf16_f32 v10, v74, v75
	v_cvt_pk_bf16_f32 v11, v76, v77
	global_store_dwordx4 v[60:61], v[4:7], off
	global_store_dwordx4 v[60:61], v[8:11], off offset:16
	s_cmpk_gt_i32 s2, 0x41ff
	s_cbranch_scc0 .Lat_q

; __global__ void __launch_bounds__(512, 2) mega_fwd(Args a) {
;     extern __shared__ __attribute__((aligned(16))) unsigned char lds[];
;     cg::grid_group grid = cg::this_grid();
;     const int tid = threadIdx.x, lane = tid & 63, wave = __builtin_amdgcn_readfirstlane(tid >> 6);
	.amdhsa_kernel _Z8mega_fwd4Args
		.amdhsa_group_segment_fixed_size 0
		.amdhsa_private_segment_fixed_size 0
		.amdhsa_kernarg_size 472
		.amdhsa_user_sgpr_count 2
		.amdhsa_user_sgpr_dispatch_ptr 0
		.amdhsa_user_sgpr_queue_ptr 0
		.amdhsa_user_sgpr_kernarg_segment_ptr 1
		.amdhsa_user_sgpr_dispatch_id 0
		.amdhsa_user_sgpr_kernarg_preload_length 0
		.amdhsa_user_sgpr_kernarg_preload_offset 0
		.amdhsa_user_sgpr_private_segment_size 0
		.amdhsa_uses_dynamic_stack 0
		.amdhsa_enable_private_segment 0
		.amdhsa_system_sgpr_workgroup_id_x 1
		.amdhsa_system_sgpr_workgroup_id_y 0
		.amdhsa_system_sgpr_workgroup_id_z 0
		.amdhsa_system_sgpr_workgroup_info 0
		.amdhsa_system_vgpr_workitem_id 2
		.amdhsa_next_free_vgpr 256
		.amdhsa_next_free_sgpr 102
		.amdhsa_accum_offset 256
		.amdhsa_reserve_vcc 1
		.amdhsa_float_round_mode_32 0
		.amdhsa_float_round_mode_16_64 0
		.amdhsa_float_denorm_mode_32 3
		.amdhsa_float_denorm_mode_16_64 3
		.amdhsa_dx10_clamp 1
		.amdhsa_ieee_mode 1
		.amdhsa_fp16_overflow 0
		.amdhsa_tg_split 0
		.amdhsa_exception_fp_ieee_invalid_op 0
		.amdhsa_exception_fp_denorm_src 0
		.amdhsa_exception_fp_ieee_div_zero 0
		.amdhsa_exception_fp_ieee_overflow 0
		.amdhsa_exception_fp_ieee_underflow 0
		.amdhsa_exception_fp_ieee_inexact 0
		.amdhsa_exception_int_div_zero 0
	.end_amdhsa_kernel

; __global__ void __launch_bounds__(512, 2) mega_fwd(Args a) {
;     extern __shared__ __attribute__((aligned(16))) unsigned char lds[];
;     cg::grid_group grid = cg::this_grid();
;     const int tid = threadIdx.x, lane = tid & 63, wave = __builtin_amdgcn_readfirstlane(tid >> 6);
amdhsa.kernels:
  - .agpr_count:     0
    .args:
      - .offset:         0
        .size:           216
        .value_kind:     by_value
      - .offset:         216
        .size:           4
        .value_kind:     hidden_block_count_x
      - .offset:         220
        .size:           4
        .value_kind:     hidden_block_count_y
      - .offset:         224
        .size:           4
        .value_kind:     hidden_block_count_z
      - .offset:         228
        .size:           2
        .value_kind:     hidden_group_size_x
      - .offset:         230
        .size:           2
        .value_kind:     hidden_group_size_y
      - .offset:         232
        .size:           2
        .value_kind:     hidden_group_size_z
      - .offset:         234
        .size:           2
        .value_kind:     hidden_remainder_x
      - .offset:         236
        .size:           2
        .value_kind:     hidden_remainder_y
      - .offset:         238
        .size:           2
        .value_kind:     hidden_remainder_z
      - .offset:         256
        .size:           8
        .value_kind:     hidden_global_offset_x
      - .offset:         264
        .size:           8
        .value_kind:     hidden_global_offset_y
      - .offset:         272
        .size:           8
        .value_kind:     hidden_global_offset_z
      - .offset:         280
        .size:           2
        .value_kind:     hidden_grid_dims
      - .offset:         304
        .size:           8
        .value_kind:     hidden_multigrid_sync_arg
      - .offset:         336
        .size:           4
        .value_kind:     hidden_dynamic_lds_size
    .group_segment_fixed_size: 0
    .kernarg_segment_align: 8
    .kernarg_segment_size: 472
    .language:       OpenCL C
    .language_version:
      - 2
      - 0
    .max_flat_workgroup_size: 512
    .name:           _Z8mega_fwd4Args
    .private_segment_fixed_size: 0
    .sgpr_count:     108
    .sgpr_spill_count: 71
    .symbol:         _Z8mega_fwd4Args.kd
    .uniform_work_group_size: 1
    .uses_dynamic_stack: false
    .vgpr_count:     256
    .vgpr_spill_count: 0
    .wavefront_size: 64
